# stack3: + LDS-DMA stage loads in the K-loops use SGPR-base + 32-bit VGPR offset (no per-load 64-bit VALU address add), + RowExchange L1 invalidate issued before polling
# baseline (speedup 1.0000x reference)
; #define PG8_STAGE(bufoff, gbase, voff) do { _Pragma("unroll") for (int _i = 0; _i < 2; ++_i) \
;         __builtin_amdgcn_global_load_lds((const unsigned*)((const char*)(gbase) + (voff)[_i]), (PG8_LAS unsigned*)(lds + (bufoff) + ldsw + _i * 8192), 16, 0, 0); } while (0)
; #define PG8_LDA(dst, b, h) do { _Pragma("unroll") for (int m = 0; m < 4; ++m) _Pragma("unroll") for (int k = 0; k < 2; ++k) dst[m][k] = *(const PG8_LAS bf16x8*)(lds + PG8_SA(b, h) + aoff + m * 2048 + k * 1024); } while (0)
; #define PG8_LDB(dst, b, h) do { _Pragma("unroll") for (int n = 0; n < 2; ++n) _Pragma("unroll") for (int k = 0; k < 2; ++k) dst[n][k] = *(const PG8_LAS bf16x8*)(lds + PG8_SB(b, h) + boff + n * 2048 + k * 1024); } while (0)
; #define PG8_MMA(ai, bj, At, Bt) do { __builtin_amdgcn_s_setprio(1); _Pragma("unroll") for (int m = 0; m < 4; ++m) _Pragma("unroll") for (int n = 0; n < 2; ++n) _Pragma("unroll") for (int k = 0; k < 2; ++k) \
;         acc[ai][bj][m][n] = __builtin_amdgcn_mfma_f32_16x16x32_bf16(Bt[n][k], At[m][k], acc[ai][bj][m][n], 0, 0, 0); __builtin_amdgcn_s_setprio(0); } while (0)
; #define PG8_WAIT_V(n) asm volatile("s_waitcnt vmcnt(" #n ")" ::: "memory")
; #define PG8_BAR __builtin_amdgcn_s_barrier()
; template <class Epi, class Sched, bool ALIGN_EPI = false, bool SP2 = false>
; __device__ __forceinline__ void gemm_phase(PG8_LAS unsigned char* lds, const Gemm g, const Sched& S, const Epi& E, int tid_in) {
;     ...
;         for (int t = tb_; t < te_; t += 2) {
;             const bool last = (t == nt - 2);
;             const char* a1 = cA + (size_t)(t + 1) * kstep;
;             const char* a2 = last ? nA : cA + (size_t)(t + 2) * kstep; const char* b2 = last ? nB : cB + (size_t)(t + 2) * kstep;
;             const char* a3 = a2 + kstep; const char* b3 = b2 + kstep;
;             if (last && has_next) S.a_ready(nxt);
;             if constexpr (SP2) {
;             PG8_LDB(B0, 0, 0); PG8_LDB(B1, 0, 1); PG8_SCHED; PG8_LDA(At, 0, 0); PG8_STAGE(PG8_SA(1, 1), a1 + hstep, voffA);
;             PG8_WAIT_V(8); PG8_WAIT_L(0); PG8_BAR; PG8_MMA(0, 0, At, B0); PG8_MMA(0, 1, At, B1); PG8_BAR; PG8_SCHED;
;             PG8_LDA(At, 0, 1); PG8_STAGE(PG8_SB(0, 0), b2, voffB); PG8_STAGE(PG8_SB(0, 1), b2 + hstep, voffB); PG8_STAGE(PG8_SA(0, 0), a2, voffA);
;             PG8_WAIT_V(8); PG8_WAIT_L(0); PG8_BAR; PG8_MMA(1, 0, At, B0); PG8_MMA(1, 1, At, B1); PG8_BAR; PG8_SCHED;
.LBB0_74:
	s_add_u32 s30, s24, 0x100
	s_addc_u32 s31, s25, 0
	s_mov_b32 s44, -2
	s_waitcnt vmcnt(0)
	s_add_u32 s24, s22, 0x100
	s_addc_u32 s25, s23, 0
	s_add_i32 s45, 0, 0x10000
	s_cmp_eq_u32 s44, 40
	s_cselect_b32 s29, s61, s25
	s_cselect_b32 s28, s60, s24
	s_cselect_b32 s27, s21, s31
	s_cselect_b32 s26, s20, s30
	s_add_i32 s48, 0, 0x14000
	v_add_u32_e32 v152, s45, v159
	v_add_u32_e32 v156, s48, v159
	ds_read_b128 v[130:133], v152
	ds_read_b128 v[134:137], v152 offset:1024
	ds_read_b128 v[148:151], v152 offset:2048
	ds_read_b128 v[152:155], v152 offset:3072
	ds_read_b128 v[180:183], v156
	ds_read_b128 v[184:187], v156 offset:1024
	ds_read_b128 v[188:191], v156 offset:2048
	ds_read_b128 v[192:195], v156 offset:3072
	v_lshl_add_u64 v[156:157], s[22:23], 0, v[144:145]
	s_add_i32 m0, s62, 0xc000
	ds_read_b128 v[196:199], v178
	ds_read_b128 v[200:203], v178 offset:1024
	ds_read_b128 v[204:207], v178 offset:2048
	ds_read_b128 v[208:211], v178 offset:3072
	ds_read_b128 v[212:215], v178 offset:4096
	ds_read_b128 v[216:219], v178 offset:5120
	ds_read_b128 v[220:223], v178 offset:6144
	ds_read_b128 v[242:245], v178 offset:7168
	global_load_lds_dwordx4 v[156:157], off
	v_lshl_add_u64 v[156:157], s[22:23], 0, v[146:147]
	s_add_i32 m0, s62, 0xe000
	s_nop 0
	global_load_lds_dwordx4 v[156:157], off
	s_waitcnt vmcnt(8)
	s_waitcnt lgkmcnt(0)
	s_barrier
	s_setprio 1
	s_waitcnt lgkmcnt(0)
	v_mfma_f32_16x16x32_bf16 v[126:129], v[130:133], v[196:199], 0
	v_mfma_f32_16x16x32_bf16 v[122:125], v[148:151], v[196:199], 0
	v_mfma_f32_16x16x32_bf16 v[110:113], v[130:133], v[204:207], 0
	v_mfma_f32_16x16x32_bf16 v[106:109], v[148:151], v[204:207], 0
	v_mfma_f32_16x16x32_bf16 v[94:97], v[130:133], v[212:215], 0
	v_mfma_f32_16x16x32_bf16 v[90:93], v[148:151], v[212:215], 0
	v_mfma_f32_16x16x32_bf16 v[78:81], v[130:133], v[220:223], 0
	v_mfma_f32_16x16x32_bf16 v[74:77], v[148:151], v[220:223], 0
	v_mfma_f32_16x16x32_bf16 v[126:129], v[134:137], v[200:203], v[126:129]
	v_mfma_f32_16x16x32_bf16 v[122:125], v[152:155], v[200:203], v[122:125]
	v_mfma_f32_16x16x32_bf16 v[110:113], v[134:137], v[208:211], v[110:113]
	v_mfma_f32_16x16x32_bf16 v[106:109], v[152:155], v[208:211], v[106:109]
	v_mfma_f32_16x16x32_bf16 v[94:97], v[134:137], v[216:219], v[94:97]
	v_mfma_f32_16x16x32_bf16 v[90:93], v[152:155], v[216:219], v[90:93]
	v_mfma_f32_16x16x32_bf16 v[78:81], v[134:137], v[242:245], v[78:81]
	v_mfma_f32_16x16x32_bf16 v[74:77], v[152:155], v[242:245], v[74:77]
	v_mfma_f32_16x16x32_bf16 v[118:121], v[180:183], v[196:199], 0
	v_mfma_f32_16x16x32_bf16 v[114:117], v[188:191], v[196:199], 0
	v_mfma_f32_16x16x32_bf16 v[102:105], v[180:183], v[204:207], 0
	v_mfma_f32_16x16x32_bf16 v[98:101], v[188:191], v[204:207], 0
	v_mfma_f32_16x16x32_bf16 v[86:89], v[180:183], v[212:215], 0
	v_mfma_f32_16x16x32_bf16 v[82:85], v[188:191], v[212:215], 0
	v_mfma_f32_16x16x32_bf16 v[70:73], v[180:183], v[220:223], 0
	v_mfma_f32_16x16x32_bf16 v[66:69], v[188:191], v[220:223], 0
	v_mfma_f32_16x16x32_bf16 v[118:121], v[184:187], v[200:203], v[118:121]
	v_mfma_f32_16x16x32_bf16 v[114:117], v[192:195], v[200:203], v[114:117]
	v_mfma_f32_16x16x32_bf16 v[102:105], v[184:187], v[208:211], v[102:105]
	v_mfma_f32_16x16x32_bf16 v[98:101], v[192:195], v[208:211], v[98:101]
	v_mfma_f32_16x16x32_bf16 v[86:89], v[184:187], v[216:219], v[86:89]
	v_mfma_f32_16x16x32_bf16 v[82:85], v[192:195], v[216:219], v[82:85]
	v_mfma_f32_16x16x32_bf16 v[70:73], v[184:187], v[242:245], v[70:73]
	v_mfma_f32_16x16x32_bf16 v[66:69], v[192:195], v[242:245], v[66:69]
	s_setprio 0
	s_barrier
	s_add_i32 s22, s45, s37
	v_lshl_add_u64 v[156:157], s[26:27], 0, v[64:65]
	s_mov_b32 m0, s22
	ds_read_b128 v[196:199], v178 offset:16384
	ds_read_b128 v[200:203], v178 offset:17408
	ds_read_b128 v[204:207], v178 offset:18432
	ds_read_b128 v[208:211], v178 offset:19456
	ds_read_b128 v[212:215], v178 offset:20480
	ds_read_b128 v[216:219], v178 offset:21504
	ds_read_b128 v[220:223], v178 offset:22528
	ds_read_b128 v[242:245], v178 offset:23552
	global_load_lds_dwordx4 v64, s[26:27]
	s_add_i32 m0, s22, 0x2000
	s_add_u32 s22, s26, 0xb0000
	v_lshl_add_u64 v[172:173], s[26:27], 0, v[142:143]
	s_addc_u32 s23, s27, 0
	s_add_i32 s45, s48, s37
	global_load_lds_dwordx4 v142, s[26:27]
	s_mov_b32 m0, s45
	v_lshl_add_u64 v[232:233], s[28:29], 0, v[140:141]
	global_load_lds_dwordx4 v64, s[22:23]
	s_add_i32 m0, s45, 0x2000
	s_nop 0
	global_load_lds_dwordx4 v142, s[22:23]
	v_lshl_add_u64 v[224:225], s[28:29], 0, v[138:139]
	s_mov_b32 m0, s62
	s_nop 0
	global_load_lds_dwordx4 v138, s[28:29]
	s_mov_b32 m0, s63
	s_nop 0
	global_load_lds_dwordx4 v140, s[28:29]
	s_waitcnt vmcnt(8)
	s_waitcnt lgkmcnt(0)
	s_barrier
; #define PG8_STAGE(bufoff, gbase, voff) do { _Pragma("unroll") for (int _i = 0; _i < 2; ++_i) \
;         __builtin_amdgcn_global_load_lds((const unsigned*)((const char*)(gbase) + (voff)[_i]), (PG8_LAS unsigned*)(lds + (bufoff) + ldsw + _i * 8192), 16, 0, 0); } while (0)
; #define PG8_LDA(dst, b, h) do { _Pragma("unroll") for (int m = 0; m < 4; ++m) _Pragma("unroll") for (int k = 0; k < 2; ++k) dst[m][k] = *(const PG8_LAS bf16x8*)(lds + PG8_SA(b, h) + aoff + m * 2048 + k * 1024); } while (0)
; #define PG8_LDB(dst, b, h) do { _Pragma("unroll") for (int n = 0; n < 2; ++n) _Pragma("unroll") for (int k = 0; k < 2; ++k) dst[n][k] = *(const PG8_LAS bf16x8*)(lds + PG8_SB(b, h) + boff + n * 2048 + k * 1024); } while (0)
; #define PG8_MMA(ai, bj, At, Bt) do { __builtin_amdgcn_s_setprio(1); _Pragma("unroll") for (int m = 0; m < 4; ++m) _Pragma("unroll") for (int n = 0; n < 2; ++n) _Pragma("unroll") for (int k = 0; k < 2; ++k) \
;         acc[ai][bj][m][n] = __builtin_amdgcn_mfma_f32_16x16x32_bf16(Bt[n][k], At[m][k], acc[ai][bj][m][n], 0, 0, 0); __builtin_amdgcn_s_setprio(0); } while (0)
; #define PG8_WAIT_V(n) asm volatile("s_waitcnt vmcnt(" #n ")" ::: "memory")
; #define PG8_WAIT_L(n) asm volatile("s_waitcnt lgkmcnt(" #n ")" ::: "memory")
; #define PG8_BAR __builtin_amdgcn_s_barrier()
; #define PG8_SCHED __builtin_amdgcn_sched_barrier(0)
; template <class Epi, class Sched, bool ALIGN_EPI = false, bool SP2 = false>
; __device__ __forceinline__ void gemm_phase(PG8_LAS unsigned char* lds, const Gemm g, const Sched& S, const Epi& E, int tid_in) {
;     ...
;             PG8_WAIT_V(8); PG8_WAIT_L(0); PG8_BAR; PG8_MMA(1, 0, At, B0); PG8_MMA(1, 1, At, B1); PG8_BAR; PG8_SCHED;
;             PG8_LDB(B0, 1, 0); PG8_LDB(B1, 1, 1); PG8_SCHED; PG8_LDA(At, 1, 0); PG8_STAGE(PG8_SA(0, 1), a2 + hstep, voffA);
;             PG8_WAIT_V(8); PG8_WAIT_L(0); PG8_BAR; PG8_MMA(0, 0, At, B0); PG8_MMA(0, 1, At, B1); PG8_BAR; PG8_SCHED;
	s_setprio 1
	s_waitcnt lgkmcnt(0)
	v_mfma_f32_16x16x32_bf16 v[60:63], v[130:133], v[196:199], 0
	v_mfma_f32_16x16x32_bf16 v[56:59], v[148:151], v[196:199], 0
	v_mfma_f32_16x16x32_bf16 v[44:47], v[130:133], v[204:207], 0
	v_mfma_f32_16x16x32_bf16 v[40:43], v[148:151], v[204:207], 0
	v_mfma_f32_16x16x32_bf16 v[28:31], v[130:133], v[212:215], 0
	v_mfma_f32_16x16x32_bf16 v[24:27], v[148:151], v[212:215], 0
	v_mfma_f32_16x16x32_bf16 v[12:15], v[130:133], v[220:223], 0
	v_mfma_f32_16x16x32_bf16 v[8:11], v[148:151], v[220:223], 0
	v_mfma_f32_16x16x32_bf16 v[60:63], v[134:137], v[200:203], v[60:63]
	v_mfma_f32_16x16x32_bf16 v[56:59], v[152:155], v[200:203], v[56:59]
	v_mfma_f32_16x16x32_bf16 v[44:47], v[134:137], v[208:211], v[44:47]
	v_mfma_f32_16x16x32_bf16 v[40:43], v[152:155], v[208:211], v[40:43]
	v_mfma_f32_16x16x32_bf16 v[28:31], v[134:137], v[216:219], v[28:31]
	v_mfma_f32_16x16x32_bf16 v[24:27], v[152:155], v[216:219], v[24:27]
	v_mfma_f32_16x16x32_bf16 v[12:15], v[134:137], v[242:245], v[12:15]
	v_mfma_f32_16x16x32_bf16 v[8:11], v[152:155], v[242:245], v[8:11]
	v_mfma_f32_16x16x32_bf16 v[52:55], v[180:183], v[196:199], 0
	v_mfma_f32_16x16x32_bf16 v[48:51], v[188:191], v[196:199], 0
	v_mfma_f32_16x16x32_bf16 v[36:39], v[180:183], v[204:207], 0
	v_mfma_f32_16x16x32_bf16 v[32:35], v[188:191], v[204:207], 0
	v_mfma_f32_16x16x32_bf16 v[20:23], v[180:183], v[212:215], 0
	v_mfma_f32_16x16x32_bf16 v[16:19], v[188:191], v[212:215], 0
	v_mfma_f32_16x16x32_bf16 v[4:7], v[180:183], v[220:223], 0
	v_mfma_f32_16x16x32_bf16 v[0:3], v[188:191], v[220:223], 0
	v_mfma_f32_16x16x32_bf16 v[52:55], v[184:187], v[200:203], v[52:55]
	v_mfma_f32_16x16x32_bf16 v[48:51], v[192:195], v[200:203], v[48:51]
	v_mfma_f32_16x16x32_bf16 v[36:39], v[184:187], v[208:211], v[36:39]
	v_mfma_f32_16x16x32_bf16 v[32:35], v[192:195], v[208:211], v[32:35]
	v_mfma_f32_16x16x32_bf16 v[20:23], v[184:187], v[216:219], v[20:23]
	v_mfma_f32_16x16x32_bf16 v[16:19], v[192:195], v[216:219], v[16:19]
	v_mfma_f32_16x16x32_bf16 v[4:7], v[184:187], v[242:245], v[4:7]
	v_mfma_f32_16x16x32_bf16 v[0:3], v[192:195], v[242:245], v[0:3]
	s_setprio 0
	s_barrier
	s_add_i32 s45, 0, 0x18000
	s_add_i32 s48, 0, 0x1c000
	v_add_u32_e32 v152, s45, v159
	v_add_u32_e32 v179, s48, v159
	ds_read_b128 v[130:133], v152
	ds_read_b128 v[134:137], v152 offset:1024
	ds_read_b128 v[148:151], v152 offset:2048
	ds_read_b128 v[152:155], v152 offset:3072
	ds_read_b128 v[180:183], v179
	ds_read_b128 v[184:187], v179 offset:1024
	ds_read_b128 v[188:191], v179 offset:2048
	ds_read_b128 v[192:195], v179 offset:3072
	s_add_u32 s22, s28, 0xb0000
	s_addc_u32 s23, s29, 0
	s_mov_b32 m0, s66
	ds_read_b128 v[196:199], v178 offset:32768
	ds_read_b128 v[200:203], v178 offset:33792
	ds_read_b128 v[204:207], v178 offset:34816
	ds_read_b128 v[208:211], v178 offset:35840
	ds_read_b128 v[212:215], v178 offset:36864
	ds_read_b128 v[216:219], v178 offset:37888
	ds_read_b128 v[220:223], v178 offset:38912
	ds_read_b128 v[242:245], v178 offset:39936
	global_load_lds_dwordx4 v138, s[22:23]
	s_mov_b32 m0, s67
	s_nop 0
	global_load_lds_dwordx4 v140, s[22:23]
	s_waitcnt vmcnt(8)
	s_waitcnt lgkmcnt(0)
	s_barrier
	s_setprio 1
	s_waitcnt lgkmcnt(0)
	v_mfma_f32_16x16x32_bf16 v[126:129], v[130:133], v[196:199], v[126:129]
	v_mfma_f32_16x16x32_bf16 v[122:125], v[148:151], v[196:199], v[122:125]
	v_mfma_f32_16x16x32_bf16 v[110:113], v[130:133], v[204:207], v[110:113]
	v_mfma_f32_16x16x32_bf16 v[106:109], v[148:151], v[204:207], v[106:109]
	v_mfma_f32_16x16x32_bf16 v[94:97], v[130:133], v[212:215], v[94:97]
	v_mfma_f32_16x16x32_bf16 v[90:93], v[148:151], v[212:215], v[90:93]
	v_mfma_f32_16x16x32_bf16 v[78:81], v[130:133], v[220:223], v[78:81]
	v_mfma_f32_16x16x32_bf16 v[74:77], v[148:151], v[220:223], v[74:77]
	v_mfma_f32_16x16x32_bf16 v[126:129], v[134:137], v[200:203], v[126:129]
	v_mfma_f32_16x16x32_bf16 v[122:125], v[152:155], v[200:203], v[122:125]
	v_mfma_f32_16x16x32_bf16 v[110:113], v[134:137], v[208:211], v[110:113]
	v_mfma_f32_16x16x32_bf16 v[106:109], v[152:155], v[208:211], v[106:109]
	v_mfma_f32_16x16x32_bf16 v[94:97], v[134:137], v[216:219], v[94:97]
	v_mfma_f32_16x16x32_bf16 v[90:93], v[152:155], v[216:219], v[90:93]
	v_mfma_f32_16x16x32_bf16 v[78:81], v[134:137], v[242:245], v[78:81]
	v_mfma_f32_16x16x32_bf16 v[74:77], v[152:155], v[242:245], v[74:77]
	v_mfma_f32_16x16x32_bf16 v[118:121], v[180:183], v[196:199], v[118:121]
	v_mfma_f32_16x16x32_bf16 v[114:117], v[188:191], v[196:199], v[114:117]
	v_mfma_f32_16x16x32_bf16 v[102:105], v[180:183], v[204:207], v[102:105]
	v_mfma_f32_16x16x32_bf16 v[98:101], v[188:191], v[204:207], v[98:101]
	v_mfma_f32_16x16x32_bf16 v[86:89], v[180:183], v[212:215], v[86:89]
	v_mfma_f32_16x16x32_bf16 v[82:85], v[188:191], v[212:215], v[82:85]
	v_mfma_f32_16x16x32_bf16 v[70:73], v[180:183], v[220:223], v[70:73]
	v_mfma_f32_16x16x32_bf16 v[66:69], v[188:191], v[220:223], v[66:69]
	v_mfma_f32_16x16x32_bf16 v[118:121], v[184:187], v[200:203], v[118:121]
	v_mfma_f32_16x16x32_bf16 v[114:117], v[192:195], v[200:203], v[114:117]
	v_mfma_f32_16x16x32_bf16 v[102:105], v[184:187], v[208:211], v[102:105]
	v_mfma_f32_16x16x32_bf16 v[98:101], v[192:195], v[208:211], v[98:101]
	v_mfma_f32_16x16x32_bf16 v[86:89], v[184:187], v[216:219], v[86:89]
	v_mfma_f32_16x16x32_bf16 v[82:85], v[192:195], v[216:219], v[82:85]
	v_mfma_f32_16x16x32_bf16 v[70:73], v[184:187], v[242:245], v[70:73]
	v_mfma_f32_16x16x32_bf16 v[66:69], v[192:195], v[242:245], v[66:69]
	s_setprio 0
	s_barrier
; #define PG8_STAGE(bufoff, gbase, voff) do { _Pragma("unroll") for (int _i = 0; _i < 2; ++_i) \
;         __builtin_amdgcn_global_load_lds((const unsigned*)((const char*)(gbase) + (voff)[_i]), (PG8_LAS unsigned*)(lds + (bufoff) + ldsw + _i * 8192), 16, 0, 0); } while (0)
; #define PG8_LDA(dst, b, h) do { _Pragma("unroll") for (int m = 0; m < 4; ++m) _Pragma("unroll") for (int k = 0; k < 2; ++k) dst[m][k] = *(const PG8_LAS bf16x8*)(lds + PG8_SA(b, h) + aoff + m * 2048 + k * 1024); } while (0)
; #define PG8_LDB(dst, b, h) do { _Pragma("unroll") for (int n = 0; n < 2; ++n) _Pragma("unroll") for (int k = 0; k < 2; ++k) dst[n][k] = *(const PG8_LAS bf16x8*)(lds + PG8_SB(b, h) + boff + n * 2048 + k * 1024); } while (0)
; #define PG8_MMA(ai, bj, At, Bt) do { __builtin_amdgcn_s_setprio(1); _Pragma("unroll") for (int m = 0; m < 4; ++m) _Pragma("unroll") for (int n = 0; n < 2; ++n) _Pragma("unroll") for (int k = 0; k < 2; ++k) \
;         acc[ai][bj][m][n] = __builtin_amdgcn_mfma_f32_16x16x32_bf16(Bt[n][k], At[m][k], acc[ai][bj][m][n], 0, 0, 0); __builtin_amdgcn_s_setprio(0); } while (0)
; #define PG8_WAIT_V(n) asm volatile("s_waitcnt vmcnt(" #n ")" ::: "memory")
; #define PG8_BAR __builtin_amdgcn_s_barrier()
; template <class Epi, class Sched, bool ALIGN_EPI = false, bool SP2 = false>
; __device__ __forceinline__ void gemm_phase(PG8_LAS unsigned char* lds, const Gemm g, const Sched& S, const Epi& E, int tid_in) {
;     ...
;         for (int t = tb_; t < te_; t += 2) {
;             const bool last = (t == nt - 2);
;             const char* a1 = cA + (size_t)(t + 1) * kstep;
;             const char* a2 = last ? nA : cA + (size_t)(t + 2) * kstep; const char* b2 = last ? nB : cB + (size_t)(t + 2) * kstep;
;             const char* a3 = a2 + kstep; const char* b3 = b2 + kstep;
;             if (last && has_next) S.a_ready(nxt);
;             if constexpr (SP2) {
;             PG8_LDB(B0, 0, 0); PG8_LDB(B1, 0, 1); PG8_SCHED; PG8_LDA(At, 0, 0); PG8_STAGE(PG8_SA(1, 1), a1 + hstep, voffA);
;             PG8_WAIT_V(8); PG8_WAIT_L(0); PG8_BAR; PG8_MMA(0, 0, At, B0); PG8_MMA(0, 1, At, B1); PG8_BAR; PG8_SCHED;
;     ...
;             PG8_LDA(At, 1, 1); PG8_STAGE(PG8_SB(1, 0), b3, voffB); PG8_STAGE(PG8_SB(1, 1), b3 + hstep, voffB); PG8_STAGE(PG8_SA(1, 0), a3, voffA);
;             PG8_WAIT_V(8); PG8_WAIT_L(0); PG8_BAR; PG8_MMA(1, 0, At, B0); PG8_MMA(1, 1, At, B1); PG8_BAR; PG8_SCHED;
	s_add_i32 s22, s45, s37
	s_mov_b32 m0, s22
	ds_read_b128 v[196:199], v178 offset:49152
	ds_read_b128 v[200:203], v178 offset:50176
	ds_read_b128 v[204:207], v178 offset:51200
	ds_read_b128 v[208:211], v178 offset:52224
	ds_read_b128 v[212:215], v178 offset:53248
	ds_read_b128 v[216:219], v178 offset:54272
	ds_read_b128 v[220:223], v178 offset:55296
	ds_read_b128 v[242:245], v178 offset:56320
	s_add_u32 s98, s26, 0x80
	s_addc_u32 s99, s27, 0
	global_load_lds_dwordx4 v64, s[98:99]
	s_add_i32 m0, s22, 0x2000
	s_add_u32 s22, s26, 0xb0080
	v_lshl_add_u64 v[156:157], v[172:173], 0, s[92:93]
	s_addc_u32 s23, s27, 0
	s_add_i32 s26, s48, s37
	global_load_lds_dwordx4 v[156:157], off
	s_mov_b32 m0, s26
	s_nop 0
	global_load_lds_dwordx4 v64, s[22:23]
	s_add_i32 m0, s26, 0x2000
	s_nop 0
	global_load_lds_dwordx4 v142, s[22:23]
	s_mov_b32 m0, s69
	s_nop 0
	s_add_u32 s98, s28, 0x80
	s_addc_u32 s99, s29, 0
	global_load_lds_dwordx4 v138, s[98:99]
	s_mov_b32 m0, s74
	s_nop 0
	s_add_u32 s98, s28, 0x80
	s_addc_u32 s99, s29, 0
	global_load_lds_dwordx4 v140, s[98:99]
	s_waitcnt vmcnt(8)
	s_waitcnt lgkmcnt(0)
	s_barrier
	s_setprio 1
	s_waitcnt lgkmcnt(0)
	v_mfma_f32_16x16x32_bf16 v[60:63], v[130:133], v[196:199], v[60:63]
	v_mfma_f32_16x16x32_bf16 v[56:59], v[148:151], v[196:199], v[56:59]
	v_mfma_f32_16x16x32_bf16 v[44:47], v[130:133], v[204:207], v[44:47]
	v_mfma_f32_16x16x32_bf16 v[40:43], v[148:151], v[204:207], v[40:43]
	v_mfma_f32_16x16x32_bf16 v[28:31], v[130:133], v[212:215], v[28:31]
	v_mfma_f32_16x16x32_bf16 v[24:27], v[148:151], v[212:215], v[24:27]
	v_mfma_f32_16x16x32_bf16 v[12:15], v[130:133], v[220:223], v[12:15]
	v_mfma_f32_16x16x32_bf16 v[8:11], v[148:151], v[220:223], v[8:11]
	v_mfma_f32_16x16x32_bf16 v[60:63], v[134:137], v[200:203], v[60:63]
	v_mfma_f32_16x16x32_bf16 v[56:59], v[152:155], v[200:203], v[56:59]
	v_mfma_f32_16x16x32_bf16 v[44:47], v[134:137], v[208:211], v[44:47]
	v_mfma_f32_16x16x32_bf16 v[40:43], v[152:155], v[208:211], v[40:43]
	v_mfma_f32_16x16x32_bf16 v[28:31], v[134:137], v[216:219], v[28:31]
	v_mfma_f32_16x16x32_bf16 v[24:27], v[152:155], v[216:219], v[24:27]
	v_mfma_f32_16x16x32_bf16 v[12:15], v[134:137], v[242:245], v[12:15]
	v_mfma_f32_16x16x32_bf16 v[8:11], v[152:155], v[242:245], v[8:11]
	v_mfma_f32_16x16x32_bf16 v[52:55], v[180:183], v[196:199], v[52:55]
	v_mfma_f32_16x16x32_bf16 v[48:51], v[188:191], v[196:199], v[48:51]
	v_mfma_f32_16x16x32_bf16 v[36:39], v[180:183], v[204:207], v[36:39]
	v_mfma_f32_16x16x32_bf16 v[32:35], v[188:191], v[204:207], v[32:35]
	v_mfma_f32_16x16x32_bf16 v[20:23], v[180:183], v[212:215], v[20:23]
	v_mfma_f32_16x16x32_bf16 v[16:19], v[188:191], v[212:215], v[16:19]
	v_mfma_f32_16x16x32_bf16 v[4:7], v[180:183], v[220:223], v[4:7]
	v_mfma_f32_16x16x32_bf16 v[0:3], v[188:191], v[220:223], v[0:3]
	v_mfma_f32_16x16x32_bf16 v[52:55], v[184:187], v[200:203], v[52:55]
	v_mfma_f32_16x16x32_bf16 v[48:51], v[192:195], v[200:203], v[48:51]
	v_mfma_f32_16x16x32_bf16 v[36:39], v[184:187], v[208:211], v[36:39]
	v_mfma_f32_16x16x32_bf16 v[32:35], v[192:195], v[208:211], v[32:35]
	v_mfma_f32_16x16x32_bf16 v[20:23], v[184:187], v[216:219], v[20:23]
	v_mfma_f32_16x16x32_bf16 v[16:19], v[192:195], v[216:219], v[16:19]
	v_mfma_f32_16x16x32_bf16 v[4:7], v[184:187], v[242:245], v[4:7]
	v_mfma_f32_16x16x32_bf16 v[0:3], v[192:195], v[242:245], v[0:3]
	s_setprio 0
	s_barrier
	s_add_i32 s44, s44, 2
	s_add_u32 s30, s30, 0x100
	s_addc_u32 s31, s31, 0
	s_cmp_gt_u32 s44, 41
	s_mov_b64 s[22:23], s[24:25]
	s_cbranch_scc0 .LBB0_75
	s_branch .Lpeel_exit_2
.LBB0_75:
	s_add_u32 s24, s22, 0x100
	s_addc_u32 s25, s23, 0
	s_add_i32 s45, 0, 0x10000
	s_cmp_eq_u32 s44, 40
	s_cselect_b32 s29, s61, s25
	s_cselect_b32 s28, s60, s24
	s_cselect_b32 s27, s21, s31
	s_cselect_b32 s26, s20, s30
	s_add_i32 s48, 0, 0x14000
	v_add_u32_e32 v152, s45, v159
	v_add_u32_e32 v156, s48, v159
	ds_read_b128 v[130:133], v152
	ds_read_b128 v[134:137], v152 offset:1024
	ds_read_b128 v[148:151], v152 offset:2048
	ds_read_b128 v[152:155], v152 offset:3072
	ds_read_b128 v[180:183], v156
	ds_read_b128 v[184:187], v156 offset:1024
	ds_read_b128 v[188:191], v156 offset:2048
	ds_read_b128 v[192:195], v156 offset:3072
	v_lshl_add_u64 v[156:157], s[22:23], 0, v[144:145]
	s_add_i32 m0, s62, 0xc000
	ds_read_b128 v[196:199], v178
	ds_read_b128 v[200:203], v178 offset:1024
	ds_read_b128 v[204:207], v178 offset:2048
	ds_read_b128 v[208:211], v178 offset:3072
	ds_read_b128 v[212:215], v178 offset:4096
	ds_read_b128 v[216:219], v178 offset:5120
	ds_read_b128 v[220:223], v178 offset:6144
	ds_read_b128 v[242:245], v178 offset:7168
	global_load_lds_dwordx4 v[156:157], off
	v_lshl_add_u64 v[156:157], s[22:23], 0, v[146:147]
	s_add_i32 m0, s62, 0xe000
	s_nop 0
	global_load_lds_dwordx4 v[156:157], off
	s_waitcnt vmcnt(8)
	s_waitcnt lgkmcnt(0)
	s_barrier
; #define PG8_STAGE(bufoff, gbase, voff) do { _Pragma("unroll") for (int _i = 0; _i < 2; ++_i) \
;         __builtin_amdgcn_global_load_lds((const unsigned*)((const char*)(gbase) + (voff)[_i]), (PG8_LAS unsigned*)(lds + (bufoff) + ldsw + _i * 8192), 16, 0, 0); } while (0)
; #define PG8_LDA(dst, b, h) do { _Pragma("unroll") for (int m = 0; m < 4; ++m) _Pragma("unroll") for (int k = 0; k < 2; ++k) dst[m][k] = *(const PG8_LAS bf16x8*)(lds + PG8_SA(b, h) + aoff + m * 2048 + k * 1024); } while (0)
; #define PG8_MMA(ai, bj, At, Bt) do { __builtin_amdgcn_s_setprio(1); _Pragma("unroll") for (int m = 0; m < 4; ++m) _Pragma("unroll") for (int n = 0; n < 2; ++n) _Pragma("unroll") for (int k = 0; k < 2; ++k) \
;         acc[ai][bj][m][n] = __builtin_amdgcn_mfma_f32_16x16x32_bf16(Bt[n][k], At[m][k], acc[ai][bj][m][n], 0, 0, 0); __builtin_amdgcn_s_setprio(0); } while (0)
; #define PG8_WAIT_V(n) asm volatile("s_waitcnt vmcnt(" #n ")" ::: "memory")
; #define PG8_WAIT_L(n) asm volatile("s_waitcnt lgkmcnt(" #n ")" ::: "memory")
; #define PG8_BAR __builtin_amdgcn_s_barrier()
; #define PG8_SCHED __builtin_amdgcn_sched_barrier(0)
; template <class Epi, class Sched, bool ALIGN_EPI = false, bool SP2 = false>
; __device__ __forceinline__ void gemm_phase(PG8_LAS unsigned char* lds, const Gemm g, const Sched& S, const Epi& E, int tid_in) {
;     ...
;             PG8_WAIT_V(8); PG8_WAIT_L(0); PG8_BAR; PG8_MMA(0, 0, At, B0); PG8_MMA(0, 1, At, B1); PG8_BAR; PG8_SCHED;
;             PG8_LDA(At, 0, 1); PG8_STAGE(PG8_SB(0, 0), b2, voffB); PG8_STAGE(PG8_SB(0, 1), b2 + hstep, voffB); PG8_STAGE(PG8_SA(0, 0), a2, voffA);
;             PG8_WAIT_V(8); PG8_WAIT_L(0); PG8_BAR; PG8_MMA(1, 0, At, B0); PG8_MMA(1, 1, At, B1); PG8_BAR; PG8_SCHED;
	s_setprio 1
	s_waitcnt lgkmcnt(0)
	v_mfma_f32_16x16x32_bf16 v[126:129], v[130:133], v[196:199], v[126:129]
	v_mfma_f32_16x16x32_bf16 v[122:125], v[148:151], v[196:199], v[122:125]
	v_mfma_f32_16x16x32_bf16 v[110:113], v[130:133], v[204:207], v[110:113]
	v_mfma_f32_16x16x32_bf16 v[106:109], v[148:151], v[204:207], v[106:109]
	v_mfma_f32_16x16x32_bf16 v[94:97], v[130:133], v[212:215], v[94:97]
	v_mfma_f32_16x16x32_bf16 v[90:93], v[148:151], v[212:215], v[90:93]
	v_mfma_f32_16x16x32_bf16 v[78:81], v[130:133], v[220:223], v[78:81]
	v_mfma_f32_16x16x32_bf16 v[74:77], v[148:151], v[220:223], v[74:77]
	v_mfma_f32_16x16x32_bf16 v[126:129], v[134:137], v[200:203], v[126:129]
	v_mfma_f32_16x16x32_bf16 v[122:125], v[152:155], v[200:203], v[122:125]
	v_mfma_f32_16x16x32_bf16 v[110:113], v[134:137], v[208:211], v[110:113]
	v_mfma_f32_16x16x32_bf16 v[106:109], v[152:155], v[208:211], v[106:109]
	v_mfma_f32_16x16x32_bf16 v[94:97], v[134:137], v[216:219], v[94:97]
	v_mfma_f32_16x16x32_bf16 v[90:93], v[152:155], v[216:219], v[90:93]
	v_mfma_f32_16x16x32_bf16 v[78:81], v[134:137], v[242:245], v[78:81]
	v_mfma_f32_16x16x32_bf16 v[74:77], v[152:155], v[242:245], v[74:77]
	v_mfma_f32_16x16x32_bf16 v[118:121], v[180:183], v[196:199], v[118:121]
	v_mfma_f32_16x16x32_bf16 v[114:117], v[188:191], v[196:199], v[114:117]
	v_mfma_f32_16x16x32_bf16 v[102:105], v[180:183], v[204:207], v[102:105]
	v_mfma_f32_16x16x32_bf16 v[98:101], v[188:191], v[204:207], v[98:101]
	v_mfma_f32_16x16x32_bf16 v[86:89], v[180:183], v[212:215], v[86:89]
	v_mfma_f32_16x16x32_bf16 v[82:85], v[188:191], v[212:215], v[82:85]
	v_mfma_f32_16x16x32_bf16 v[70:73], v[180:183], v[220:223], v[70:73]
	v_mfma_f32_16x16x32_bf16 v[66:69], v[188:191], v[220:223], v[66:69]
	v_mfma_f32_16x16x32_bf16 v[118:121], v[184:187], v[200:203], v[118:121]
	v_mfma_f32_16x16x32_bf16 v[114:117], v[192:195], v[200:203], v[114:117]
	v_mfma_f32_16x16x32_bf16 v[102:105], v[184:187], v[208:211], v[102:105]
	v_mfma_f32_16x16x32_bf16 v[98:101], v[192:195], v[208:211], v[98:101]
	v_mfma_f32_16x16x32_bf16 v[86:89], v[184:187], v[216:219], v[86:89]
	v_mfma_f32_16x16x32_bf16 v[82:85], v[192:195], v[216:219], v[82:85]
	v_mfma_f32_16x16x32_bf16 v[70:73], v[184:187], v[242:245], v[70:73]
	v_mfma_f32_16x16x32_bf16 v[66:69], v[192:195], v[242:245], v[66:69]
	s_setprio 0
	s_barrier
	s_add_i32 s22, s45, s37
	v_lshl_add_u64 v[156:157], s[26:27], 0, v[64:65]
	s_mov_b32 m0, s22
	ds_read_b128 v[196:199], v178 offset:16384
	ds_read_b128 v[200:203], v178 offset:17408
	ds_read_b128 v[204:207], v178 offset:18432
	ds_read_b128 v[208:211], v178 offset:19456
	ds_read_b128 v[212:215], v178 offset:20480
	ds_read_b128 v[216:219], v178 offset:21504
	ds_read_b128 v[220:223], v178 offset:22528
	ds_read_b128 v[242:245], v178 offset:23552
	global_load_lds_dwordx4 v64, s[26:27]
	s_add_i32 m0, s22, 0x2000
	s_add_u32 s22, s26, 0xb0000
	v_lshl_add_u64 v[172:173], s[26:27], 0, v[142:143]
	s_addc_u32 s23, s27, 0
	s_add_i32 s45, s48, s37
	global_load_lds_dwordx4 v142, s[26:27]
	s_mov_b32 m0, s45
	v_lshl_add_u64 v[232:233], s[28:29], 0, v[140:141]
	global_load_lds_dwordx4 v64, s[22:23]
	s_add_i32 m0, s45, 0x2000
	s_nop 0
	global_load_lds_dwordx4 v142, s[22:23]
	v_lshl_add_u64 v[224:225], s[28:29], 0, v[138:139]
	s_mov_b32 m0, s62
	s_nop 0
	global_load_lds_dwordx4 v138, s[28:29]
	s_mov_b32 m0, s63
	s_nop 0
	global_load_lds_dwordx4 v140, s[28:29]
	s_waitcnt vmcnt(8)
	s_waitcnt lgkmcnt(0)
	s_barrier
	s_setprio 1
	s_waitcnt lgkmcnt(0)
	v_mfma_f32_16x16x32_bf16 v[60:63], v[130:133], v[196:199], v[60:63]
	v_mfma_f32_16x16x32_bf16 v[56:59], v[148:151], v[196:199], v[56:59]
	v_mfma_f32_16x16x32_bf16 v[44:47], v[130:133], v[204:207], v[44:47]
	v_mfma_f32_16x16x32_bf16 v[40:43], v[148:151], v[204:207], v[40:43]
	v_mfma_f32_16x16x32_bf16 v[28:31], v[130:133], v[212:215], v[28:31]
	v_mfma_f32_16x16x32_bf16 v[24:27], v[148:151], v[212:215], v[24:27]
	v_mfma_f32_16x16x32_bf16 v[12:15], v[130:133], v[220:223], v[12:15]
	v_mfma_f32_16x16x32_bf16 v[8:11], v[148:151], v[220:223], v[8:11]
	v_mfma_f32_16x16x32_bf16 v[60:63], v[134:137], v[200:203], v[60:63]
	v_mfma_f32_16x16x32_bf16 v[56:59], v[152:155], v[200:203], v[56:59]
	v_mfma_f32_16x16x32_bf16 v[44:47], v[134:137], v[208:211], v[44:47]
	v_mfma_f32_16x16x32_bf16 v[40:43], v[152:155], v[208:211], v[40:43]
	v_mfma_f32_16x16x32_bf16 v[28:31], v[134:137], v[216:219], v[28:31]
	v_mfma_f32_16x16x32_bf16 v[24:27], v[152:155], v[216:219], v[24:27]
	v_mfma_f32_16x16x32_bf16 v[12:15], v[134:137], v[242:245], v[12:15]
	v_mfma_f32_16x16x32_bf16 v[8:11], v[152:155], v[242:245], v[8:11]
	v_mfma_f32_16x16x32_bf16 v[52:55], v[180:183], v[196:199], v[52:55]
	v_mfma_f32_16x16x32_bf16 v[48:51], v[188:191], v[196:199], v[48:51]
	v_mfma_f32_16x16x32_bf16 v[36:39], v[180:183], v[204:207], v[36:39]
	v_mfma_f32_16x16x32_bf16 v[32:35], v[188:191], v[204:207], v[32:35]
	v_mfma_f32_16x16x32_bf16 v[20:23], v[180:183], v[212:215], v[20:23]
	v_mfma_f32_16x16x32_bf16 v[16:19], v[188:191], v[212:215], v[16:19]
	v_mfma_f32_16x16x32_bf16 v[4:7], v[180:183], v[220:223], v[4:7]
	v_mfma_f32_16x16x32_bf16 v[0:3], v[188:191], v[220:223], v[0:3]
	v_mfma_f32_16x16x32_bf16 v[52:55], v[184:187], v[200:203], v[52:55]
	v_mfma_f32_16x16x32_bf16 v[48:51], v[192:195], v[200:203], v[48:51]
	v_mfma_f32_16x16x32_bf16 v[36:39], v[184:187], v[208:211], v[36:39]
	v_mfma_f32_16x16x32_bf16 v[32:35], v[192:195], v[208:211], v[32:35]
	v_mfma_f32_16x16x32_bf16 v[20:23], v[184:187], v[216:219], v[20:23]
	v_mfma_f32_16x16x32_bf16 v[16:19], v[192:195], v[216:219], v[16:19]
	v_mfma_f32_16x16x32_bf16 v[4:7], v[184:187], v[242:245], v[4:7]
	v_mfma_f32_16x16x32_bf16 v[0:3], v[192:195], v[242:245], v[0:3]
	s_setprio 0
	s_barrier
; #define PG8_STAGE(bufoff, gbase, voff) do { _Pragma("unroll") for (int _i = 0; _i < 2; ++_i) \
;         __builtin_amdgcn_global_load_lds((const unsigned*)((const char*)(gbase) + (voff)[_i]), (PG8_LAS unsigned*)(lds + (bufoff) + ldsw + _i * 8192), 16, 0, 0); } while (0)
; #define PG8_LDA(dst, b, h) do { _Pragma("unroll") for (int m = 0; m < 4; ++m) _Pragma("unroll") for (int k = 0; k < 2; ++k) dst[m][k] = *(const PG8_LAS bf16x8*)(lds + PG8_SA(b, h) + aoff + m * 2048 + k * 1024); } while (0)
; #define PG8_LDB(dst, b, h) do { _Pragma("unroll") for (int n = 0; n < 2; ++n) _Pragma("unroll") for (int k = 0; k < 2; ++k) dst[n][k] = *(const PG8_LAS bf16x8*)(lds + PG8_SB(b, h) + boff + n * 2048 + k * 1024); } while (0)
; #define PG8_MMA(ai, bj, At, Bt) do { __builtin_amdgcn_s_setprio(1); _Pragma("unroll") for (int m = 0; m < 4; ++m) _Pragma("unroll") for (int n = 0; n < 2; ++n) _Pragma("unroll") for (int k = 0; k < 2; ++k) \
;         acc[ai][bj][m][n] = __builtin_amdgcn_mfma_f32_16x16x32_bf16(Bt[n][k], At[m][k], acc[ai][bj][m][n], 0, 0, 0); __builtin_amdgcn_s_setprio(0); } while (0)
; #define PG8_WAIT_V(n) asm volatile("s_waitcnt vmcnt(" #n ")" ::: "memory")
; #define PG8_WAIT_L(n) asm volatile("s_waitcnt lgkmcnt(" #n ")" ::: "memory")
; #define PG8_BAR __builtin_amdgcn_s_barrier()
; #define PG8_SCHED __builtin_amdgcn_sched_barrier(0)
; template <class Epi, class Sched, bool ALIGN_EPI = false, bool SP2 = false>
; __device__ __forceinline__ void gemm_phase(PG8_LAS unsigned char* lds, const Gemm g, const Sched& S, const Epi& E, int tid_in) {
;     ...
;             PG8_LDB(B0, 1, 0); PG8_LDB(B1, 1, 1); PG8_SCHED; PG8_LDA(At, 1, 0); PG8_STAGE(PG8_SA(0, 1), a2 + hstep, voffA);
;             PG8_WAIT_V(8); PG8_WAIT_L(0); PG8_BAR; PG8_MMA(0, 0, At, B0); PG8_MMA(0, 1, At, B1); PG8_BAR; PG8_SCHED;
;             PG8_LDA(At, 1, 1); PG8_STAGE(PG8_SB(1, 0), b3, voffB); PG8_STAGE(PG8_SB(1, 1), b3 + hstep, voffB); PG8_STAGE(PG8_SA(1, 0), a3, voffA);
;             PG8_WAIT_V(8); PG8_WAIT_L(0); PG8_BAR; PG8_MMA(1, 0, At, B0); PG8_MMA(1, 1, At, B1); PG8_BAR; PG8_SCHED;
	s_add_i32 s45, 0, 0x18000
	s_add_i32 s48, 0, 0x1c000
	v_add_u32_e32 v152, s45, v159
	v_add_u32_e32 v179, s48, v159
	ds_read_b128 v[130:133], v152
	ds_read_b128 v[134:137], v152 offset:1024
	ds_read_b128 v[148:151], v152 offset:2048
	ds_read_b128 v[152:155], v152 offset:3072
	ds_read_b128 v[180:183], v179
	ds_read_b128 v[184:187], v179 offset:1024
	ds_read_b128 v[188:191], v179 offset:2048
	ds_read_b128 v[192:195], v179 offset:3072
	s_add_u32 s22, s28, 0xb0000
	s_addc_u32 s23, s29, 0
	s_mov_b32 m0, s66
	ds_read_b128 v[196:199], v178 offset:32768
	ds_read_b128 v[200:203], v178 offset:33792
	ds_read_b128 v[204:207], v178 offset:34816
	ds_read_b128 v[208:211], v178 offset:35840
	ds_read_b128 v[212:215], v178 offset:36864
	ds_read_b128 v[216:219], v178 offset:37888
	ds_read_b128 v[220:223], v178 offset:38912
	ds_read_b128 v[242:245], v178 offset:39936
	global_load_lds_dwordx4 v138, s[22:23]
	s_mov_b32 m0, s67
	s_nop 0
	global_load_lds_dwordx4 v140, s[22:23]
	s_waitcnt vmcnt(8)
	s_waitcnt lgkmcnt(0)
	s_barrier
	s_setprio 1
	s_waitcnt lgkmcnt(0)
	v_mfma_f32_16x16x32_bf16 v[126:129], v[130:133], v[196:199], v[126:129]
	v_mfma_f32_16x16x32_bf16 v[122:125], v[148:151], v[196:199], v[122:125]
	v_mfma_f32_16x16x32_bf16 v[110:113], v[130:133], v[204:207], v[110:113]
	v_mfma_f32_16x16x32_bf16 v[106:109], v[148:151], v[204:207], v[106:109]
	v_mfma_f32_16x16x32_bf16 v[94:97], v[130:133], v[212:215], v[94:97]
	v_mfma_f32_16x16x32_bf16 v[90:93], v[148:151], v[212:215], v[90:93]
	v_mfma_f32_16x16x32_bf16 v[78:81], v[130:133], v[220:223], v[78:81]
	v_mfma_f32_16x16x32_bf16 v[74:77], v[148:151], v[220:223], v[74:77]
	v_mfma_f32_16x16x32_bf16 v[126:129], v[134:137], v[200:203], v[126:129]
	v_mfma_f32_16x16x32_bf16 v[122:125], v[152:155], v[200:203], v[122:125]
	v_mfma_f32_16x16x32_bf16 v[110:113], v[134:137], v[208:211], v[110:113]
	v_mfma_f32_16x16x32_bf16 v[106:109], v[152:155], v[208:211], v[106:109]
	v_mfma_f32_16x16x32_bf16 v[94:97], v[134:137], v[216:219], v[94:97]
	v_mfma_f32_16x16x32_bf16 v[90:93], v[152:155], v[216:219], v[90:93]
	v_mfma_f32_16x16x32_bf16 v[78:81], v[134:137], v[242:245], v[78:81]
	v_mfma_f32_16x16x32_bf16 v[74:77], v[152:155], v[242:245], v[74:77]
	v_mfma_f32_16x16x32_bf16 v[118:121], v[180:183], v[196:199], v[118:121]
	v_mfma_f32_16x16x32_bf16 v[114:117], v[188:191], v[196:199], v[114:117]
	v_mfma_f32_16x16x32_bf16 v[102:105], v[180:183], v[204:207], v[102:105]
	v_mfma_f32_16x16x32_bf16 v[98:101], v[188:191], v[204:207], v[98:101]
	v_mfma_f32_16x16x32_bf16 v[86:89], v[180:183], v[212:215], v[86:89]
	v_mfma_f32_16x16x32_bf16 v[82:85], v[188:191], v[212:215], v[82:85]
	v_mfma_f32_16x16x32_bf16 v[70:73], v[180:183], v[220:223], v[70:73]
	v_mfma_f32_16x16x32_bf16 v[66:69], v[188:191], v[220:223], v[66:69]
	v_mfma_f32_16x16x32_bf16 v[118:121], v[184:187], v[200:203], v[118:121]
	v_mfma_f32_16x16x32_bf16 v[114:117], v[192:195], v[200:203], v[114:117]
	v_mfma_f32_16x16x32_bf16 v[102:105], v[184:187], v[208:211], v[102:105]
	v_mfma_f32_16x16x32_bf16 v[98:101], v[192:195], v[208:211], v[98:101]
	v_mfma_f32_16x16x32_bf16 v[86:89], v[184:187], v[216:219], v[86:89]
	v_mfma_f32_16x16x32_bf16 v[82:85], v[192:195], v[216:219], v[82:85]
	v_mfma_f32_16x16x32_bf16 v[70:73], v[184:187], v[242:245], v[70:73]
	v_mfma_f32_16x16x32_bf16 v[66:69], v[192:195], v[242:245], v[66:69]
	s_setprio 0
	s_barrier
	s_add_i32 s22, s45, s37
	s_mov_b32 m0, s22
	ds_read_b128 v[196:199], v178 offset:49152
	ds_read_b128 v[200:203], v178 offset:50176
	ds_read_b128 v[204:207], v178 offset:51200
	ds_read_b128 v[208:211], v178 offset:52224
	ds_read_b128 v[212:215], v178 offset:53248
	ds_read_b128 v[216:219], v178 offset:54272
	ds_read_b128 v[220:223], v178 offset:55296
	ds_read_b128 v[242:245], v178 offset:56320
	s_add_u32 s98, s26, 0x80
	s_addc_u32 s99, s27, 0
	global_load_lds_dwordx4 v64, s[98:99]
	s_add_i32 m0, s22, 0x2000
	s_add_u32 s22, s26, 0xb0080
	v_lshl_add_u64 v[156:157], v[172:173], 0, s[92:93]
	s_addc_u32 s23, s27, 0
	s_add_i32 s26, s48, s37
	global_load_lds_dwordx4 v[156:157], off
	s_mov_b32 m0, s26
	s_nop 0
	global_load_lds_dwordx4 v64, s[22:23]
	s_add_i32 m0, s26, 0x2000
	s_nop 0
	global_load_lds_dwordx4 v142, s[22:23]
	s_mov_b32 m0, s69
	s_nop 0
	s_add_u32 s98, s28, 0x80
	s_addc_u32 s99, s29, 0
	global_load_lds_dwordx4 v138, s[98:99]
	s_mov_b32 m0, s74
	s_nop 0
	s_add_u32 s98, s28, 0x80
	s_addc_u32 s99, s29, 0
	global_load_lds_dwordx4 v140, s[98:99]
	s_waitcnt vmcnt(8)
	s_waitcnt lgkmcnt(0)
	s_barrier
	s_setprio 1
	s_waitcnt lgkmcnt(0)
	v_mfma_f32_16x16x32_bf16 v[60:63], v[130:133], v[196:199], v[60:63]
	v_mfma_f32_16x16x32_bf16 v[56:59], v[148:151], v[196:199], v[56:59]
	v_mfma_f32_16x16x32_bf16 v[44:47], v[130:133], v[204:207], v[44:47]
	v_mfma_f32_16x16x32_bf16 v[40:43], v[148:151], v[204:207], v[40:43]
	v_mfma_f32_16x16x32_bf16 v[28:31], v[130:133], v[212:215], v[28:31]
	v_mfma_f32_16x16x32_bf16 v[24:27], v[148:151], v[212:215], v[24:27]
	v_mfma_f32_16x16x32_bf16 v[12:15], v[130:133], v[220:223], v[12:15]
	v_mfma_f32_16x16x32_bf16 v[8:11], v[148:151], v[220:223], v[8:11]
	v_mfma_f32_16x16x32_bf16 v[60:63], v[134:137], v[200:203], v[60:63]
	v_mfma_f32_16x16x32_bf16 v[56:59], v[152:155], v[200:203], v[56:59]
	v_mfma_f32_16x16x32_bf16 v[44:47], v[134:137], v[208:211], v[44:47]
	v_mfma_f32_16x16x32_bf16 v[40:43], v[152:155], v[208:211], v[40:43]
	v_mfma_f32_16x16x32_bf16 v[28:31], v[134:137], v[216:219], v[28:31]
	v_mfma_f32_16x16x32_bf16 v[24:27], v[152:155], v[216:219], v[24:27]
	v_mfma_f32_16x16x32_bf16 v[12:15], v[134:137], v[242:245], v[12:15]
	v_mfma_f32_16x16x32_bf16 v[8:11], v[152:155], v[242:245], v[8:11]
	v_mfma_f32_16x16x32_bf16 v[52:55], v[180:183], v[196:199], v[52:55]
	v_mfma_f32_16x16x32_bf16 v[48:51], v[188:191], v[196:199], v[48:51]
	v_mfma_f32_16x16x32_bf16 v[36:39], v[180:183], v[204:207], v[36:39]
	v_mfma_f32_16x16x32_bf16 v[32:35], v[188:191], v[204:207], v[32:35]
	v_mfma_f32_16x16x32_bf16 v[20:23], v[180:183], v[212:215], v[20:23]
	v_mfma_f32_16x16x32_bf16 v[16:19], v[188:191], v[212:215], v[16:19]
	v_mfma_f32_16x16x32_bf16 v[4:7], v[180:183], v[220:223], v[4:7]
	v_mfma_f32_16x16x32_bf16 v[0:3], v[188:191], v[220:223], v[0:3]
	v_mfma_f32_16x16x32_bf16 v[52:55], v[184:187], v[200:203], v[52:55]
	v_mfma_f32_16x16x32_bf16 v[48:51], v[192:195], v[200:203], v[48:51]
	v_mfma_f32_16x16x32_bf16 v[36:39], v[184:187], v[208:211], v[36:39]
	v_mfma_f32_16x16x32_bf16 v[32:35], v[192:195], v[208:211], v[32:35]
	v_mfma_f32_16x16x32_bf16 v[20:23], v[184:187], v[216:219], v[20:23]
	v_mfma_f32_16x16x32_bf16 v[16:19], v[192:195], v[216:219], v[16:19]
	v_mfma_f32_16x16x32_bf16 v[4:7], v[184:187], v[242:245], v[4:7]
	v_mfma_f32_16x16x32_bf16 v[0:3], v[192:195], v[242:245], v[0:3]
	s_setprio 0
	s_barrier
	s_add_i32 s44, s44, 2
	s_add_u32 s30, s30, 0x100
	s_addc_u32 s31, s31, 0
	s_cmp_gt_u32 s44, 41
	s_mov_b64 s[22:23], s[24:25]
	s_cbranch_scc0 .LBB0_75

;     DI void run(const float (&part)[2][4], const pg8::Unit& u, int wr, int wc, int fr, int fq, int wid, int lane, LAS float* S, volatile LAS unsigned* flag) const {
;     ...
;         if (lane == 0) __hip_atomic_fetch_add(cnt + 64 * u.pm, 1u, __ATOMIC_RELAXED, __HIP_MEMORY_SCOPE_AGENT);
;         if (wid == 0) {
;             unsigned sp = 0;
;             for (;;) {
;                 if ((unsigned)__builtin_amdgcn_readfirstlane(__hip_atomic_load(cnt + 64 * u.pm, __ATOMIC_RELAXED, __HIP_MEMORY_SCOPE_AGENT)) >= 32u) break;
;                 __builtin_amdgcn_s_sleep(2);
;                 if (++sp > (1u << 20)) { if (lane == 0) __hip_atomic_store(tmo, 1u, __ATOMIC_RELAXED, __HIP_MEMORY_SCOPE_AGENT); break; }
;             }
.LBB0_114:
	s_or_b64 exec, exec, s[26:27]
	s_andn2_b64 vcc, exec, s[56:57]
	s_cbranch_vccnz .LBB0_124
	s_lshl_b32 s26, s36, 6
	s_ashr_i32 s27, s26, 31
	s_lshl_b64 s[26:27], s[26:27], 2
	s_add_u32 s26, s30, s26
	s_addc_u32 s27, s31, s27
	s_mov_b32 s44, 0x100001
	buffer_inv sc1
	s_branch .LBB0_117

;     DI void run(const float (&part)[2][4], const pg8::Unit& u, int wr, int wc, int fr, int fq, int wid, int lane, LAS float* S, volatile LAS unsigned* flag) const {
;     ...
;             __builtin_amdgcn_fence(__ATOMIC_ACQUIRE, "agent");
;         }
;         asm volatile("s_waitcnt vmcnt(0) lgkmcnt(0)" ::: "memory"); __builtin_amdgcn_s_barrier(); asm volatile("" ::: "memory");
;         int ln = lane; asm volatile("" : "+v"(ln));
;         if (ln < 32) {
;             const int r = wid * 32 + ln;
;             const unsigned* sl = (const unsigned*)slots + (size_t)(u.pm * 256 + r) * 16;
;             float v[16];
;             if (local) {
;                 const v4f q0 = ((const v4f*)sl)[0], q1 = ((const v4f*)sl)[1], q2 = ((const v4f*)sl)[2], q3 = ((const v4f*)sl)[3];
; #pragma unroll
;                 for (int k = 0; k < 4; ++k) { v[k] = q0[k]; v[4 + k] = q1[k]; v[8 + k] = q2[k]; v[12 + k] = q3[k]; }
;             } else {
; #pragma unroll
;                 for (int k = 0; k < 16; ++k) v[k] = __uint_as_float(__hip_atomic_load(sl + k, __ATOMIC_RELAXED, __HIP_MEMORY_SCOPE_AGENT));
.LBB0_123:
	s_waitcnt vmcnt(0) lgkmcnt(0)
.LBB0_124:
	s_waitcnt vmcnt(0) lgkmcnt(0)
	s_barrier
	v_mov_b32_e32 v130, v161
	s_nop 0
	v_cmp_lt_i32_e32 vcc, 31, v130
	s_and_saveexec_b64 s[26:27], vcc
	s_xor_b64 s[26:27], exec, s[26:27]
	s_lshl_b32 s28, s36, 8
	s_or_saveexec_b64 s[26:27], s[26:27]
	v_mov_b32_e32 v152, s28
	s_xor_b64 exec, exec, s[26:27]
	s_cbranch_execz .LBB0_132
	v_add_u32_e32 v181, s79, v130
	s_lshl_b32 s28, s36, 8
	v_add_u32_e32 v130, s28, v181
	s_waitcnt lgkmcnt(0)
	v_ashrrev_i32_e32 v131, 31, v130
	v_lshlrev_b64 v[130:131], 6, v[130:131]
	v_lshl_add_u64 v[156:157], s[22:23], 0, v[130:131]
	s_andn2_b64 vcc, exec, s[52:53]
	s_mov_b64 s[22:23], -1
	s_cbranch_vccnz .LBB0_129
	global_load_dword v134, v[156:157], off sc1
	global_load_dword v154, v[156:157], off offset:4 sc1
	global_load_dword v136, v[156:157], off offset:8 sc1
	global_load_dword v152, v[156:157], off offset:12 sc1
	global_load_dword v130, v[156:157], off offset:16 sc1
	global_load_dword v150, v[156:157], off offset:20 sc1
	global_load_dword v132, v[156:157], off offset:24 sc1
	global_load_dword v148, v[156:157], off offset:28 sc1
	global_load_dword v135, v[156:157], off offset:32 sc1
	global_load_dword v155, v[156:157], off offset:36 sc1
	global_load_dword v137, v[156:157], off offset:40 sc1
	global_load_dword v153, v[156:157], off offset:44 sc1
	global_load_dword v131, v[156:157], off offset:48 sc1
	global_load_dword v151, v[156:157], off offset:52 sc1
	global_load_dword v133, v[156:157], off offset:56 sc1
	global_load_dword v149, v[156:157], off offset:60 sc1
	s_mov_b64 s[22:23], 0

; #define PG8_STAGE(bufoff, gbase, voff) do { _Pragma("unroll") for (int _i = 0; _i < 2; ++_i) \
;         __builtin_amdgcn_global_load_lds((const unsigned*)((const char*)(gbase) + (voff)[_i]), (PG8_LAS unsigned*)(lds + (bufoff) + ldsw + _i * 8192), 16, 0, 0); } while (0)
; #define PG8_LDA(dst, b, h) do { _Pragma("unroll") for (int m = 0; m < 4; ++m) _Pragma("unroll") for (int k = 0; k < 2; ++k) dst[m][k] = *(const PG8_LAS bf16x8*)(lds + PG8_SA(b, h) + aoff + m * 2048 + k * 1024); } while (0)
; #define PG8_LDB(dst, b, h) do { _Pragma("unroll") for (int n = 0; n < 2; ++n) _Pragma("unroll") for (int k = 0; k < 2; ++k) dst[n][k] = *(const PG8_LAS bf16x8*)(lds + PG8_SB(b, h) + boff + n * 2048 + k * 1024); } while (0)
; template <class Epi, class Sched, bool ALIGN_EPI = false, bool SP2 = false>
; __device__ __forceinline__ void gemm_phase(PG8_LAS unsigned char* lds, const Gemm g, const Sched& S, const Epi& E, int tid_in) {
;     ...
;         const bool has_next = S.next(ui + 1, nxt);
;         const char* nA = has_next ? g.apanel(nxt.pm, tstep) : cA; const char* nB = has_next ? (const char*)g.Bt + (size_t)nxt.pn * tstep : cB;
;         for (int seg = 0; seg < (Epi::KSEG ? 3 : 1); ++seg) {
;         if constexpr (Epi::KSEG) { if (seg > 0) E.kscale(acc, seg, cur, wr, fr); }
;         const int tb_ = Epi::KSEG ? (seg == 0 ? 0 : (seg == 1 ? 8 : 12)) : 0, te_ = Epi::KSEG ? (seg == 0 ? 8 : (seg == 1 ? 12 : nt)) : nt;
; #pragma unroll 1
;         for (int t = tb_; t < te_; t += 2) {
;             const bool last = (t == nt - 2);
;             const char* a1 = cA + (size_t)(t + 1) * kstep;
;             const char* a2 = last ? nA : cA + (size_t)(t + 2) * kstep; const char* b2 = last ? nB : cB + (size_t)(t + 2) * kstep;
;             const char* a3 = a2 + kstep; const char* b3 = b2 + kstep;
;             if (last && has_next) S.a_ready(nxt);
;             if constexpr (SP2) {
;             PG8_LDB(B0, 0, 0); PG8_LDB(B1, 0, 1); PG8_SCHED; PG8_LDA(At, 0, 0); PG8_STAGE(PG8_SA(1, 1), a1 + hstep, voffA);
;             PG8_WAIT_V(8); PG8_WAIT_L(0); PG8_BAR; PG8_MMA(0, 0, At, B0); PG8_MMA(0, 1, At, B1); PG8_BAR; PG8_SCHED;
;             PG8_LDA(At, 0, 1); PG8_STAGE(PG8_SB(0, 0), b2, voffB); PG8_STAGE(PG8_SB(0, 1), b2 + hstep, voffB); PG8_STAGE(PG8_SA(0, 0), a2, voffA);
;             PG8_WAIT_V(8); PG8_WAIT_L(0); PG8_BAR; PG8_MMA(1, 0, At, B0); PG8_MMA(1, 1, At, B1); PG8_BAR; PG8_SCHED;
.LBB0_241:
	s_ashr_i32 s51, s50, 31
	s_lshl_b64 s[30:31], s[50:51], 19
	s_add_u32 s56, s37, s30
	s_addc_u32 s57, s62, s31
	s_and_b64 s[30:31], s[40:41], exec
	s_cselect_b32 s23, s57, s27
	s_cselect_b32 s25, s56, s26
	s_ashr_i32 s49, s48, 31
	s_lshl_b64 s[30:31], s[48:49], 19
	s_add_u32 s60, s63, s30
	s_addc_u32 s61, s66, s31
	s_and_b64 s[30:31], s[40:41], exec
	s_cselect_b32 s34, s61, s29
	s_cselect_b32 s35, s60, s28
	s_add_u32 s26, s26, 0x40080
	s_addc_u32 s27, s27, 0
	s_add_u32 s42, s28, 0x100
	s_addc_u32 s43, s29, 0
	s_mov_b32 s44, -2
	s_waitcnt vmcnt(0)
	s_add_u32 s28, s26, 0xfffc0080
	s_addc_u32 s29, s27, -1
	s_add_i32 s45, 0, 0x10000
	s_cmp_eq_u32 s44, 12
	s_cselect_b32 s31, s23, s29
	s_cselect_b32 s30, s25, s28
	v_add_u32_e32 v64, s45, v171
	s_cselect_b32 s29, s34, s43
	s_cselect_b32 s28, s35, s42
	s_add_i32 s49, 0, 0x14000
	ds_read_b128 v[122:125], v64
	ds_read_b128 v[126:129], v64 offset:1024
	ds_read_b128 v[130:133], v64 offset:2048
	ds_read_b128 v[134:137], v64 offset:3072
	v_add_u32_e32 v64, s49, v171
	ds_read_b128 v[146:149], v64
	ds_read_b128 v[150:153], v64 offset:1024
	ds_read_b128 v[154:157], v64 offset:2048
	ds_read_b128 v[158:161], v64 offset:3072
	s_add_i32 m0, s67, 0xc000
	ds_read_b128 v[162:165], v216
	ds_read_b128 v[166:169], v216 offset:1024
	ds_read_b128 v[192:195], v216 offset:2048
	ds_read_b128 v[196:199], v216 offset:3072
	ds_read_b128 v[200:203], v216 offset:4096
	ds_read_b128 v[204:207], v216 offset:5120
	ds_read_b128 v[208:211], v216 offset:6144
	ds_read_b128 v[212:215], v216 offset:7168
	global_load_lds_dwordx4 v188, s[26:27]
	s_add_i32 m0, s67, 0xe000
	s_nop 0
	global_load_lds_dwordx4 v190, s[26:27]
	s_waitcnt vmcnt(8)
	s_waitcnt lgkmcnt(0)
	s_barrier
	s_setprio 1
	s_waitcnt lgkmcnt(0)
	v_mfma_f32_16x16x32_bf16 v[114:117], v[122:125], v[162:165], 0
	v_mfma_f32_16x16x32_bf16 v[106:109], v[130:133], v[162:165], 0
	v_mfma_f32_16x16x32_bf16 v[142:145], v[122:125], v[192:195], 0
	v_mfma_f32_16x16x32_bf16 v[44:47], v[130:133], v[192:195], 0
	v_mfma_f32_16x16x32_bf16 v[110:113], v[122:125], v[200:203], 0
	v_mfma_f32_16x16x32_bf16 v[36:39], v[130:133], v[200:203], 0
	v_mfma_f32_16x16x32_bf16 v[118:121], v[122:125], v[208:211], 0
	v_mfma_f32_16x16x32_bf16 v[52:55], v[130:133], v[208:211], 0
	v_mfma_f32_16x16x32_bf16 v[114:117], v[126:129], v[166:169], v[114:117]
	v_mfma_f32_16x16x32_bf16 v[106:109], v[134:137], v[166:169], v[106:109]
	v_mfma_f32_16x16x32_bf16 v[142:145], v[126:129], v[196:199], v[142:145]
	v_mfma_f32_16x16x32_bf16 v[44:47], v[134:137], v[196:199], v[44:47]
	v_mfma_f32_16x16x32_bf16 v[110:113], v[126:129], v[204:207], v[110:113]
	v_mfma_f32_16x16x32_bf16 v[36:39], v[134:137], v[204:207], v[36:39]
	v_mfma_f32_16x16x32_bf16 v[118:121], v[126:129], v[212:215], v[118:121]
	v_mfma_f32_16x16x32_bf16 v[52:55], v[134:137], v[212:215], v[52:55]
	v_mfma_f32_16x16x32_bf16 v[102:105], v[146:149], v[162:165], 0
	v_mfma_f32_16x16x32_bf16 v[78:81], v[154:157], v[162:165], 0
	v_mfma_f32_16x16x32_bf16 v[138:141], v[146:149], v[192:195], 0
	v_mfma_f32_16x16x32_bf16 v[40:43], v[154:157], v[192:195], 0
	v_mfma_f32_16x16x32_bf16 v[98:101], v[146:149], v[200:203], 0
	v_mfma_f32_16x16x32_bf16 v[32:35], v[154:157], v[200:203], 0
	v_mfma_f32_16x16x32_bf16 v[94:97], v[146:149], v[208:211], 0
	v_mfma_f32_16x16x32_bf16 v[48:51], v[154:157], v[208:211], 0
	v_mfma_f32_16x16x32_bf16 v[102:105], v[150:153], v[166:169], v[102:105]
	v_mfma_f32_16x16x32_bf16 v[78:81], v[158:161], v[166:169], v[78:81]
	v_mfma_f32_16x16x32_bf16 v[138:141], v[150:153], v[196:199], v[138:141]
	v_mfma_f32_16x16x32_bf16 v[40:43], v[158:161], v[196:199], v[40:43]
	v_mfma_f32_16x16x32_bf16 v[98:101], v[150:153], v[204:207], v[98:101]
	v_mfma_f32_16x16x32_bf16 v[32:35], v[158:161], v[204:207], v[32:35]
	v_mfma_f32_16x16x32_bf16 v[94:97], v[150:153], v[212:215], v[94:97]
	v_mfma_f32_16x16x32_bf16 v[48:51], v[158:161], v[212:215], v[48:51]
	s_setprio 0
	s_barrier
	s_add_i32 s45, s45, s9
	v_lshl_add_u64 v[172:173], s[28:29], 0, v[178:179]
	s_mov_b32 m0, s45
	ds_read_b128 v[162:165], v216 offset:16384
	ds_read_b128 v[166:169], v216 offset:17408
	ds_read_b128 v[192:195], v216 offset:18432
	ds_read_b128 v[196:199], v216 offset:19456
	ds_read_b128 v[200:203], v216 offset:20480
	ds_read_b128 v[204:207], v216 offset:21504
	ds_read_b128 v[208:211], v216 offset:22528
	ds_read_b128 v[212:215], v216 offset:23552
	global_load_lds_dwordx4 v178, s[28:29]
	s_add_i32 m0, s45, 0x2000
	s_add_u32 s46, s28, 0x40000
	v_lshl_add_u64 v[220:221], s[28:29], 0, v[182:183]
	s_addc_u32 s47, s29, 0
	s_add_i32 s45, s49, s9
	global_load_lds_dwordx4 v182, s[28:29]
	s_mov_b32 m0, s45
	v_lshl_add_u64 v[224:225], s[30:31], 0, v[180:181]
	global_load_lds_dwordx4 v178, s[46:47]
	s_add_i32 m0, s45, 0x2000
	s_nop 0
	global_load_lds_dwordx4 v182, s[46:47]
	v_lshl_add_u64 v[222:223], s[30:31], 0, v[176:177]
	s_mov_b32 m0, s67
	s_nop 0
	global_load_lds_dwordx4 v176, s[30:31]
	s_mov_b32 m0, s69
	s_nop 0
	global_load_lds_dwordx4 v180, s[30:31]
	s_waitcnt vmcnt(8)
	s_waitcnt lgkmcnt(0)
	s_barrier
; #define PG8_STAGE(bufoff, gbase, voff) do { _Pragma("unroll") for (int _i = 0; _i < 2; ++_i) \
;         __builtin_amdgcn_global_load_lds((const unsigned*)((const char*)(gbase) + (voff)[_i]), (PG8_LAS unsigned*)(lds + (bufoff) + ldsw + _i * 8192), 16, 0, 0); } while (0)
; #define PG8_LDA(dst, b, h) do { _Pragma("unroll") for (int m = 0; m < 4; ++m) _Pragma("unroll") for (int k = 0; k < 2; ++k) dst[m][k] = *(const PG8_LAS bf16x8*)(lds + PG8_SA(b, h) + aoff + m * 2048 + k * 1024); } while (0)
; #define PG8_LDB(dst, b, h) do { _Pragma("unroll") for (int n = 0; n < 2; ++n) _Pragma("unroll") for (int k = 0; k < 2; ++k) dst[n][k] = *(const PG8_LAS bf16x8*)(lds + PG8_SB(b, h) + boff + n * 2048 + k * 1024); } while (0)
; #define PG8_MMA(ai, bj, At, Bt) do { __builtin_amdgcn_s_setprio(1); _Pragma("unroll") for (int m = 0; m < 4; ++m) _Pragma("unroll") for (int n = 0; n < 2; ++n) _Pragma("unroll") for (int k = 0; k < 2; ++k) \
;         acc[ai][bj][m][n] = __builtin_amdgcn_mfma_f32_16x16x32_bf16(Bt[n][k], At[m][k], acc[ai][bj][m][n], 0, 0, 0); __builtin_amdgcn_s_setprio(0); } while (0)
; #define PG8_WAIT_V(n) asm volatile("s_waitcnt vmcnt(" #n ")" ::: "memory")
; #define PG8_WAIT_L(n) asm volatile("s_waitcnt lgkmcnt(" #n ")" ::: "memory")
; #define PG8_BAR __builtin_amdgcn_s_barrier()
; #define PG8_SCHED __builtin_amdgcn_sched_barrier(0)
; template <class Epi, class Sched, bool ALIGN_EPI = false, bool SP2 = false>
; __device__ __forceinline__ void gemm_phase(PG8_LAS unsigned char* lds, const Gemm g, const Sched& S, const Epi& E, int tid_in) {
;     ...
;             PG8_WAIT_V(8); PG8_WAIT_L(0); PG8_BAR; PG8_MMA(1, 0, At, B0); PG8_MMA(1, 1, At, B1); PG8_BAR; PG8_SCHED;
;             PG8_LDB(B0, 1, 0); PG8_LDB(B1, 1, 1); PG8_SCHED; PG8_LDA(At, 1, 0); PG8_STAGE(PG8_SA(0, 1), a2 + hstep, voffA);
;             PG8_WAIT_V(8); PG8_WAIT_L(0); PG8_BAR; PG8_MMA(0, 0, At, B0); PG8_MMA(0, 1, At, B1); PG8_BAR; PG8_SCHED;
	s_setprio 1
	s_waitcnt lgkmcnt(0)
	v_mfma_f32_16x16x32_bf16 v[82:85], v[122:125], v[162:165], 0
	v_mfma_f32_16x16x32_bf16 v[20:23], v[130:133], v[162:165], 0
	v_mfma_f32_16x16x32_bf16 v[70:73], v[122:125], v[192:195], 0
	v_mfma_f32_16x16x32_bf16 v[12:15], v[130:133], v[192:195], 0
	v_mfma_f32_16x16x32_bf16 v[60:63], v[122:125], v[200:203], 0
	v_mfma_f32_16x16x32_bf16 v[4:7], v[130:133], v[200:203], 0
	v_mfma_f32_16x16x32_bf16 v[90:93], v[122:125], v[208:211], 0
	v_mfma_f32_16x16x32_bf16 v[28:31], v[130:133], v[208:211], 0
	v_mfma_f32_16x16x32_bf16 v[82:85], v[126:129], v[166:169], v[82:85]
	v_mfma_f32_16x16x32_bf16 v[20:23], v[134:137], v[166:169], v[20:23]
	v_mfma_f32_16x16x32_bf16 v[70:73], v[126:129], v[196:199], v[70:73]
	v_mfma_f32_16x16x32_bf16 v[12:15], v[134:137], v[196:199], v[12:15]
	v_mfma_f32_16x16x32_bf16 v[60:63], v[126:129], v[204:207], v[60:63]
	v_mfma_f32_16x16x32_bf16 v[4:7], v[134:137], v[204:207], v[4:7]
	v_mfma_f32_16x16x32_bf16 v[90:93], v[126:129], v[212:215], v[90:93]
	v_mfma_f32_16x16x32_bf16 v[28:31], v[134:137], v[212:215], v[28:31]
	v_mfma_f32_16x16x32_bf16 v[74:77], v[146:149], v[162:165], 0
	v_mfma_f32_16x16x32_bf16 v[16:19], v[154:157], v[162:165], 0
	v_mfma_f32_16x16x32_bf16 v[66:69], v[146:149], v[192:195], 0
	v_mfma_f32_16x16x32_bf16 v[8:11], v[154:157], v[192:195], 0
	v_mfma_f32_16x16x32_bf16 v[56:59], v[146:149], v[200:203], 0
	v_mfma_f32_16x16x32_bf16 v[0:3], v[154:157], v[200:203], 0
	v_mfma_f32_16x16x32_bf16 v[86:89], v[146:149], v[208:211], 0
	v_mfma_f32_16x16x32_bf16 v[24:27], v[154:157], v[208:211], 0
	v_mfma_f32_16x16x32_bf16 v[74:77], v[150:153], v[166:169], v[74:77]
	v_mfma_f32_16x16x32_bf16 v[16:19], v[158:161], v[166:169], v[16:19]
	v_mfma_f32_16x16x32_bf16 v[66:69], v[150:153], v[196:199], v[66:69]
	v_mfma_f32_16x16x32_bf16 v[8:11], v[158:161], v[196:199], v[8:11]
	v_mfma_f32_16x16x32_bf16 v[56:59], v[150:153], v[204:207], v[56:59]
	v_mfma_f32_16x16x32_bf16 v[0:3], v[158:161], v[204:207], v[0:3]
	v_mfma_f32_16x16x32_bf16 v[86:89], v[150:153], v[212:215], v[86:89]
	v_mfma_f32_16x16x32_bf16 v[24:27], v[158:161], v[212:215], v[24:27]
	s_setprio 0
	s_barrier
	s_add_i32 s45, 0, 0x18000
	v_add_u32_e32 v64, s45, v171
	s_add_i32 s46, 0, 0x1c000
	ds_read_b128 v[122:125], v64
	ds_read_b128 v[126:129], v64 offset:1024
	ds_read_b128 v[130:133], v64 offset:2048
	ds_read_b128 v[134:137], v64 offset:3072
	v_add_u32_e32 v64, s46, v171
	ds_read_b128 v[146:149], v64
	ds_read_b128 v[150:153], v64 offset:1024
	ds_read_b128 v[154:157], v64 offset:2048
	ds_read_b128 v[158:161], v64 offset:3072
	s_add_u32 s30, s30, 0x40000
	s_addc_u32 s31, s31, 0
	s_mov_b32 m0, s79
	ds_read_b128 v[162:165], v216 offset:32768
	ds_read_b128 v[166:169], v216 offset:33792
	ds_read_b128 v[192:195], v216 offset:34816
	ds_read_b128 v[196:199], v216 offset:35840
	ds_read_b128 v[200:203], v216 offset:36864
	ds_read_b128 v[204:207], v216 offset:37888
	ds_read_b128 v[208:211], v216 offset:38912
	ds_read_b128 v[212:215], v216 offset:39936
	global_load_lds_dwordx4 v176, s[30:31]
	s_mov_b32 m0, s82
	s_nop 0
	global_load_lds_dwordx4 v180, s[30:31]
	s_waitcnt vmcnt(8)
	s_waitcnt lgkmcnt(0)
	s_barrier
	s_setprio 1
	s_waitcnt lgkmcnt(0)
	v_mfma_f32_16x16x32_bf16 v[114:117], v[122:125], v[162:165], v[114:117]
	v_mfma_f32_16x16x32_bf16 v[106:109], v[130:133], v[162:165], v[106:109]
	v_mfma_f32_16x16x32_bf16 v[142:145], v[122:125], v[192:195], v[142:145]
	v_mfma_f32_16x16x32_bf16 v[44:47], v[130:133], v[192:195], v[44:47]
	v_mfma_f32_16x16x32_bf16 v[110:113], v[122:125], v[200:203], v[110:113]
	v_mfma_f32_16x16x32_bf16 v[36:39], v[130:133], v[200:203], v[36:39]
	v_mfma_f32_16x16x32_bf16 v[118:121], v[122:125], v[208:211], v[118:121]
	v_mfma_f32_16x16x32_bf16 v[52:55], v[130:133], v[208:211], v[52:55]
	v_mfma_f32_16x16x32_bf16 v[114:117], v[126:129], v[166:169], v[114:117]
	v_mfma_f32_16x16x32_bf16 v[106:109], v[134:137], v[166:169], v[106:109]
	v_mfma_f32_16x16x32_bf16 v[142:145], v[126:129], v[196:199], v[142:145]
	v_mfma_f32_16x16x32_bf16 v[44:47], v[134:137], v[196:199], v[44:47]
	v_mfma_f32_16x16x32_bf16 v[110:113], v[126:129], v[204:207], v[110:113]
	v_mfma_f32_16x16x32_bf16 v[36:39], v[134:137], v[204:207], v[36:39]
	v_mfma_f32_16x16x32_bf16 v[118:121], v[126:129], v[212:215], v[118:121]
	v_mfma_f32_16x16x32_bf16 v[52:55], v[134:137], v[212:215], v[52:55]
	v_mfma_f32_16x16x32_bf16 v[102:105], v[146:149], v[162:165], v[102:105]
	v_mfma_f32_16x16x32_bf16 v[78:81], v[154:157], v[162:165], v[78:81]
	v_mfma_f32_16x16x32_bf16 v[138:141], v[146:149], v[192:195], v[138:141]
	v_mfma_f32_16x16x32_bf16 v[40:43], v[154:157], v[192:195], v[40:43]
	v_mfma_f32_16x16x32_bf16 v[98:101], v[146:149], v[200:203], v[98:101]
	v_mfma_f32_16x16x32_bf16 v[32:35], v[154:157], v[200:203], v[32:35]
	v_mfma_f32_16x16x32_bf16 v[94:97], v[146:149], v[208:211], v[94:97]
	v_mfma_f32_16x16x32_bf16 v[48:51], v[154:157], v[208:211], v[48:51]
	v_mfma_f32_16x16x32_bf16 v[102:105], v[150:153], v[166:169], v[102:105]
	v_mfma_f32_16x16x32_bf16 v[78:81], v[158:161], v[166:169], v[78:81]
	v_mfma_f32_16x16x32_bf16 v[138:141], v[150:153], v[196:199], v[138:141]
	v_mfma_f32_16x16x32_bf16 v[40:43], v[158:161], v[196:199], v[40:43]
	v_mfma_f32_16x16x32_bf16 v[98:101], v[150:153], v[204:207], v[98:101]
	v_mfma_f32_16x16x32_bf16 v[32:35], v[158:161], v[204:207], v[32:35]
	v_mfma_f32_16x16x32_bf16 v[94:97], v[150:153], v[212:215], v[94:97]
	v_mfma_f32_16x16x32_bf16 v[48:51], v[158:161], v[212:215], v[48:51]
	s_setprio 0
	s_barrier
; #define PG8_STAGE(bufoff, gbase, voff) do { _Pragma("unroll") for (int _i = 0; _i < 2; ++_i) \
;         __builtin_amdgcn_global_load_lds((const unsigned*)((const char*)(gbase) + (voff)[_i]), (PG8_LAS unsigned*)(lds + (bufoff) + ldsw + _i * 8192), 16, 0, 0); } while (0)
; #define PG8_LDA(dst, b, h) do { _Pragma("unroll") for (int m = 0; m < 4; ++m) _Pragma("unroll") for (int k = 0; k < 2; ++k) dst[m][k] = *(const PG8_LAS bf16x8*)(lds + PG8_SA(b, h) + aoff + m * 2048 + k * 1024); } while (0)
; #define PG8_LDB(dst, b, h) do { _Pragma("unroll") for (int n = 0; n < 2; ++n) _Pragma("unroll") for (int k = 0; k < 2; ++k) dst[n][k] = *(const PG8_LAS bf16x8*)(lds + PG8_SB(b, h) + boff + n * 2048 + k * 1024); } while (0)
; #define PG8_MMA(ai, bj, At, Bt) do { __builtin_amdgcn_s_setprio(1); _Pragma("unroll") for (int m = 0; m < 4; ++m) _Pragma("unroll") for (int n = 0; n < 2; ++n) _Pragma("unroll") for (int k = 0; k < 2; ++k) \
;         acc[ai][bj][m][n] = __builtin_amdgcn_mfma_f32_16x16x32_bf16(Bt[n][k], At[m][k], acc[ai][bj][m][n], 0, 0, 0); __builtin_amdgcn_s_setprio(0); } while (0)
; #define PG8_WAIT_V(n) asm volatile("s_waitcnt vmcnt(" #n ")" ::: "memory")
; #define PG8_BAR __builtin_amdgcn_s_barrier()
; template <class Epi, class Sched, bool ALIGN_EPI = false, bool SP2 = false>
; __device__ __forceinline__ void gemm_phase(PG8_LAS unsigned char* lds, const Gemm g, const Sched& S, const Epi& E, int tid_in) {
;     ...
;         for (int t = tb_; t < te_; t += 2) {
;             const bool last = (t == nt - 2);
;             const char* a1 = cA + (size_t)(t + 1) * kstep;
;             const char* a2 = last ? nA : cA + (size_t)(t + 2) * kstep; const char* b2 = last ? nB : cB + (size_t)(t + 2) * kstep;
;             const char* a3 = a2 + kstep; const char* b3 = b2 + kstep;
;             if (last && has_next) S.a_ready(nxt);
;             if constexpr (SP2) {
;             PG8_LDB(B0, 0, 0); PG8_LDB(B1, 0, 1); PG8_SCHED; PG8_LDA(At, 0, 0); PG8_STAGE(PG8_SA(1, 1), a1 + hstep, voffA);
;             PG8_WAIT_V(8); PG8_WAIT_L(0); PG8_BAR; PG8_MMA(0, 0, At, B0); PG8_MMA(0, 1, At, B1); PG8_BAR; PG8_SCHED;
;     ...
;             PG8_LDA(At, 1, 1); PG8_STAGE(PG8_SB(1, 0), b3, voffB); PG8_STAGE(PG8_SB(1, 1), b3 + hstep, voffB); PG8_STAGE(PG8_SA(1, 0), a3, voffA);
;             PG8_WAIT_V(8); PG8_WAIT_L(0); PG8_BAR; PG8_MMA(1, 0, At, B0); PG8_MMA(1, 1, At, B1); PG8_BAR; PG8_SCHED;
	s_add_i32 s30, s45, s9
	s_mov_b32 m0, s30
	ds_read_b128 v[162:165], v216 offset:49152
	ds_read_b128 v[166:169], v216 offset:50176
	ds_read_b128 v[192:195], v216 offset:51200
	ds_read_b128 v[196:199], v216 offset:52224
	ds_read_b128 v[200:203], v216 offset:53248
	ds_read_b128 v[204:207], v216 offset:54272
	ds_read_b128 v[208:211], v216 offset:55296
	ds_read_b128 v[212:215], v216 offset:56320
	s_add_u32 s98, s28, 0x80
	s_addc_u32 s99, s29, 0
	global_load_lds_dwordx4 v178, s[98:99]
	s_add_i32 m0, s30, 0x2000
	s_add_u32 s28, s28, 0x40080
	v_lshl_add_u64 v[172:173], v[220:221], 0, s[92:93]
	s_addc_u32 s29, s29, 0
	s_add_i32 s30, s46, s9
	global_load_lds_dwordx4 v[172:173], off
	s_mov_b32 m0, s30
	s_nop 0
	global_load_lds_dwordx4 v178, s[28:29]
	s_add_i32 m0, s30, 0x2000
	s_nop 0
	global_load_lds_dwordx4 v182, s[28:29]
	v_lshl_add_u64 v[172:173], v[222:223], 0, s[92:93]
	s_mov_b32 m0, s85
	s_nop 0
	global_load_lds_dwordx4 v[172:173], off
	v_lshl_add_u64 v[172:173], v[224:225], 0, s[92:93]
	s_mov_b32 m0, s8
	s_nop 0
	global_load_lds_dwordx4 v[172:173], off
	s_waitcnt vmcnt(8)
	s_waitcnt lgkmcnt(0)
	s_barrier
	s_setprio 1
	s_waitcnt lgkmcnt(0)
	v_mfma_f32_16x16x32_bf16 v[82:85], v[122:125], v[162:165], v[82:85]
	v_mfma_f32_16x16x32_bf16 v[20:23], v[130:133], v[162:165], v[20:23]
	v_mfma_f32_16x16x32_bf16 v[70:73], v[122:125], v[192:195], v[70:73]
	v_mfma_f32_16x16x32_bf16 v[12:15], v[130:133], v[192:195], v[12:15]
	v_mfma_f32_16x16x32_bf16 v[60:63], v[122:125], v[200:203], v[60:63]
	v_mfma_f32_16x16x32_bf16 v[4:7], v[130:133], v[200:203], v[4:7]
	v_mfma_f32_16x16x32_bf16 v[90:93], v[122:125], v[208:211], v[90:93]
	v_mfma_f32_16x16x32_bf16 v[28:31], v[130:133], v[208:211], v[28:31]
	v_mfma_f32_16x16x32_bf16 v[82:85], v[126:129], v[166:169], v[82:85]
	v_mfma_f32_16x16x32_bf16 v[20:23], v[134:137], v[166:169], v[20:23]
	v_mfma_f32_16x16x32_bf16 v[70:73], v[126:129], v[196:199], v[70:73]
	v_mfma_f32_16x16x32_bf16 v[12:15], v[134:137], v[196:199], v[12:15]
	v_mfma_f32_16x16x32_bf16 v[60:63], v[126:129], v[204:207], v[60:63]
	v_mfma_f32_16x16x32_bf16 v[4:7], v[134:137], v[204:207], v[4:7]
	v_mfma_f32_16x16x32_bf16 v[90:93], v[126:129], v[212:215], v[90:93]
	v_mfma_f32_16x16x32_bf16 v[28:31], v[134:137], v[212:215], v[28:31]
	v_mfma_f32_16x16x32_bf16 v[74:77], v[146:149], v[162:165], v[74:77]
	v_mfma_f32_16x16x32_bf16 v[16:19], v[154:157], v[162:165], v[16:19]
	v_mfma_f32_16x16x32_bf16 v[66:69], v[146:149], v[192:195], v[66:69]
	v_mfma_f32_16x16x32_bf16 v[8:11], v[154:157], v[192:195], v[8:11]
	v_mfma_f32_16x16x32_bf16 v[56:59], v[146:149], v[200:203], v[56:59]
	v_mfma_f32_16x16x32_bf16 v[0:3], v[154:157], v[200:203], v[0:3]
	v_mfma_f32_16x16x32_bf16 v[86:89], v[146:149], v[208:211], v[86:89]
	v_mfma_f32_16x16x32_bf16 v[24:27], v[154:157], v[208:211], v[24:27]
	v_mfma_f32_16x16x32_bf16 v[74:77], v[150:153], v[166:169], v[74:77]
	v_mfma_f32_16x16x32_bf16 v[16:19], v[158:161], v[166:169], v[16:19]
	v_mfma_f32_16x16x32_bf16 v[66:69], v[150:153], v[196:199], v[66:69]
	v_mfma_f32_16x16x32_bf16 v[8:11], v[158:161], v[196:199], v[8:11]
	v_mfma_f32_16x16x32_bf16 v[56:59], v[150:153], v[204:207], v[56:59]
	v_mfma_f32_16x16x32_bf16 v[0:3], v[158:161], v[204:207], v[0:3]
	v_mfma_f32_16x16x32_bf16 v[86:89], v[150:153], v[212:215], v[86:89]
	v_mfma_f32_16x16x32_bf16 v[24:27], v[158:161], v[212:215], v[24:27]
	s_setprio 0
	s_barrier
	s_add_i32 s44, s44, 2
	s_add_u32 s26, s26, 0x100
	s_addc_u32 s27, s27, 0
	s_add_u32 s42, s42, 0x100
	s_addc_u32 s43, s43, 0
	s_cmp_gt_u32 s44, 13
	s_cbranch_scc0 .LBB0_242
	s_branch .Lpeel_exit_1
.LBB0_242:
	s_add_u32 s28, s26, 0xfffc0080
	s_addc_u32 s29, s27, -1
	s_add_i32 s45, 0, 0x10000
	s_cmp_eq_u32 s44, 12
	s_cselect_b32 s31, s23, s29
	s_cselect_b32 s30, s25, s28
	v_add_u32_e32 v64, s45, v171
	s_cselect_b32 s29, s34, s43
	s_cselect_b32 s28, s35, s42
	s_add_i32 s49, 0, 0x14000
	ds_read_b128 v[122:125], v64
	ds_read_b128 v[126:129], v64 offset:1024
	ds_read_b128 v[130:133], v64 offset:2048
	ds_read_b128 v[134:137], v64 offset:3072
	v_add_u32_e32 v64, s49, v171
	ds_read_b128 v[146:149], v64
	ds_read_b128 v[150:153], v64 offset:1024
	ds_read_b128 v[154:157], v64 offset:2048
	ds_read_b128 v[158:161], v64 offset:3072
	s_add_i32 m0, s67, 0xc000
	ds_read_b128 v[162:165], v216
	ds_read_b128 v[166:169], v216 offset:1024
	ds_read_b128 v[192:195], v216 offset:2048
	ds_read_b128 v[196:199], v216 offset:3072
	ds_read_b128 v[200:203], v216 offset:4096
	ds_read_b128 v[204:207], v216 offset:5120
	ds_read_b128 v[208:211], v216 offset:6144
	ds_read_b128 v[212:215], v216 offset:7168
	global_load_lds_dwordx4 v188, s[26:27]
	s_add_i32 m0, s67, 0xe000
	s_nop 0
	global_load_lds_dwordx4 v190, s[26:27]
	s_waitcnt vmcnt(8)
	s_waitcnt lgkmcnt(0)
	s_barrier
; #define PG8_STAGE(bufoff, gbase, voff) do { _Pragma("unroll") for (int _i = 0; _i < 2; ++_i) \
;         __builtin_amdgcn_global_load_lds((const unsigned*)((const char*)(gbase) + (voff)[_i]), (PG8_LAS unsigned*)(lds + (bufoff) + ldsw + _i * 8192), 16, 0, 0); } while (0)
; #define PG8_LDA(dst, b, h) do { _Pragma("unroll") for (int m = 0; m < 4; ++m) _Pragma("unroll") for (int k = 0; k < 2; ++k) dst[m][k] = *(const PG8_LAS bf16x8*)(lds + PG8_SA(b, h) + aoff + m * 2048 + k * 1024); } while (0)
; #define PG8_MMA(ai, bj, At, Bt) do { __builtin_amdgcn_s_setprio(1); _Pragma("unroll") for (int m = 0; m < 4; ++m) _Pragma("unroll") for (int n = 0; n < 2; ++n) _Pragma("unroll") for (int k = 0; k < 2; ++k) \
;         acc[ai][bj][m][n] = __builtin_amdgcn_mfma_f32_16x16x32_bf16(Bt[n][k], At[m][k], acc[ai][bj][m][n], 0, 0, 0); __builtin_amdgcn_s_setprio(0); } while (0)
; #define PG8_WAIT_V(n) asm volatile("s_waitcnt vmcnt(" #n ")" ::: "memory")
; #define PG8_WAIT_L(n) asm volatile("s_waitcnt lgkmcnt(" #n ")" ::: "memory")
; #define PG8_BAR __builtin_amdgcn_s_barrier()
; #define PG8_SCHED __builtin_amdgcn_sched_barrier(0)
; template <class Epi, class Sched, bool ALIGN_EPI = false, bool SP2 = false>
; __device__ __forceinline__ void gemm_phase(PG8_LAS unsigned char* lds, const Gemm g, const Sched& S, const Epi& E, int tid_in) {
;     ...
;             PG8_WAIT_V(8); PG8_WAIT_L(0); PG8_BAR; PG8_MMA(0, 0, At, B0); PG8_MMA(0, 1, At, B1); PG8_BAR; PG8_SCHED;
;             PG8_LDA(At, 0, 1); PG8_STAGE(PG8_SB(0, 0), b2, voffB); PG8_STAGE(PG8_SB(0, 1), b2 + hstep, voffB); PG8_STAGE(PG8_SA(0, 0), a2, voffA);
;             PG8_WAIT_V(8); PG8_WAIT_L(0); PG8_BAR; PG8_MMA(1, 0, At, B0); PG8_MMA(1, 1, At, B1); PG8_BAR; PG8_SCHED;
	s_setprio 1
	s_waitcnt lgkmcnt(0)
	v_mfma_f32_16x16x32_bf16 v[114:117], v[122:125], v[162:165], v[114:117]
	v_mfma_f32_16x16x32_bf16 v[106:109], v[130:133], v[162:165], v[106:109]
	v_mfma_f32_16x16x32_bf16 v[142:145], v[122:125], v[192:195], v[142:145]
	v_mfma_f32_16x16x32_bf16 v[44:47], v[130:133], v[192:195], v[44:47]
	v_mfma_f32_16x16x32_bf16 v[110:113], v[122:125], v[200:203], v[110:113]
	v_mfma_f32_16x16x32_bf16 v[36:39], v[130:133], v[200:203], v[36:39]
	v_mfma_f32_16x16x32_bf16 v[118:121], v[122:125], v[208:211], v[118:121]
	v_mfma_f32_16x16x32_bf16 v[52:55], v[130:133], v[208:211], v[52:55]
	v_mfma_f32_16x16x32_bf16 v[114:117], v[126:129], v[166:169], v[114:117]
	v_mfma_f32_16x16x32_bf16 v[106:109], v[134:137], v[166:169], v[106:109]
	v_mfma_f32_16x16x32_bf16 v[142:145], v[126:129], v[196:199], v[142:145]
	v_mfma_f32_16x16x32_bf16 v[44:47], v[134:137], v[196:199], v[44:47]
	v_mfma_f32_16x16x32_bf16 v[110:113], v[126:129], v[204:207], v[110:113]
	v_mfma_f32_16x16x32_bf16 v[36:39], v[134:137], v[204:207], v[36:39]
	v_mfma_f32_16x16x32_bf16 v[118:121], v[126:129], v[212:215], v[118:121]
	v_mfma_f32_16x16x32_bf16 v[52:55], v[134:137], v[212:215], v[52:55]
	v_mfma_f32_16x16x32_bf16 v[102:105], v[146:149], v[162:165], v[102:105]
	v_mfma_f32_16x16x32_bf16 v[78:81], v[154:157], v[162:165], v[78:81]
	v_mfma_f32_16x16x32_bf16 v[138:141], v[146:149], v[192:195], v[138:141]
	v_mfma_f32_16x16x32_bf16 v[40:43], v[154:157], v[192:195], v[40:43]
	v_mfma_f32_16x16x32_bf16 v[98:101], v[146:149], v[200:203], v[98:101]
	v_mfma_f32_16x16x32_bf16 v[32:35], v[154:157], v[200:203], v[32:35]
	v_mfma_f32_16x16x32_bf16 v[94:97], v[146:149], v[208:211], v[94:97]
	v_mfma_f32_16x16x32_bf16 v[48:51], v[154:157], v[208:211], v[48:51]
	v_mfma_f32_16x16x32_bf16 v[102:105], v[150:153], v[166:169], v[102:105]
	v_mfma_f32_16x16x32_bf16 v[78:81], v[158:161], v[166:169], v[78:81]
	v_mfma_f32_16x16x32_bf16 v[138:141], v[150:153], v[196:199], v[138:141]
	v_mfma_f32_16x16x32_bf16 v[40:43], v[158:161], v[196:199], v[40:43]
	v_mfma_f32_16x16x32_bf16 v[98:101], v[150:153], v[204:207], v[98:101]
	v_mfma_f32_16x16x32_bf16 v[32:35], v[158:161], v[204:207], v[32:35]
	v_mfma_f32_16x16x32_bf16 v[94:97], v[150:153], v[212:215], v[94:97]
	v_mfma_f32_16x16x32_bf16 v[48:51], v[158:161], v[212:215], v[48:51]
	s_setprio 0
	s_barrier
	s_add_i32 s45, s45, s9
	v_lshl_add_u64 v[172:173], s[28:29], 0, v[178:179]
	s_mov_b32 m0, s45
	ds_read_b128 v[162:165], v216 offset:16384
	ds_read_b128 v[166:169], v216 offset:17408
	ds_read_b128 v[192:195], v216 offset:18432
	ds_read_b128 v[196:199], v216 offset:19456
	ds_read_b128 v[200:203], v216 offset:20480
	ds_read_b128 v[204:207], v216 offset:21504
	ds_read_b128 v[208:211], v216 offset:22528
	ds_read_b128 v[212:215], v216 offset:23552
	global_load_lds_dwordx4 v178, s[28:29]
	s_add_i32 m0, s45, 0x2000
	s_add_u32 s46, s28, 0x40000
	v_lshl_add_u64 v[220:221], s[28:29], 0, v[182:183]
	s_addc_u32 s47, s29, 0
	s_add_i32 s45, s49, s9
	global_load_lds_dwordx4 v182, s[28:29]
	s_mov_b32 m0, s45
	v_lshl_add_u64 v[224:225], s[30:31], 0, v[180:181]
	global_load_lds_dwordx4 v178, s[46:47]
	s_add_i32 m0, s45, 0x2000
	s_nop 0
	global_load_lds_dwordx4 v182, s[46:47]
	v_lshl_add_u64 v[222:223], s[30:31], 0, v[176:177]
	s_mov_b32 m0, s67
	s_nop 0
	global_load_lds_dwordx4 v176, s[30:31]
	s_mov_b32 m0, s69
	s_nop 0
	global_load_lds_dwordx4 v180, s[30:31]
	s_waitcnt vmcnt(8)
	s_waitcnt lgkmcnt(0)
	s_barrier
	s_setprio 1
	s_waitcnt lgkmcnt(0)
	v_mfma_f32_16x16x32_bf16 v[82:85], v[122:125], v[162:165], v[82:85]
	v_mfma_f32_16x16x32_bf16 v[20:23], v[130:133], v[162:165], v[20:23]
	v_mfma_f32_16x16x32_bf16 v[70:73], v[122:125], v[192:195], v[70:73]
	v_mfma_f32_16x16x32_bf16 v[12:15], v[130:133], v[192:195], v[12:15]
	v_mfma_f32_16x16x32_bf16 v[60:63], v[122:125], v[200:203], v[60:63]
	v_mfma_f32_16x16x32_bf16 v[4:7], v[130:133], v[200:203], v[4:7]
	v_mfma_f32_16x16x32_bf16 v[90:93], v[122:125], v[208:211], v[90:93]
	v_mfma_f32_16x16x32_bf16 v[28:31], v[130:133], v[208:211], v[28:31]
	v_mfma_f32_16x16x32_bf16 v[82:85], v[126:129], v[166:169], v[82:85]
	v_mfma_f32_16x16x32_bf16 v[20:23], v[134:137], v[166:169], v[20:23]
	v_mfma_f32_16x16x32_bf16 v[70:73], v[126:129], v[196:199], v[70:73]
	v_mfma_f32_16x16x32_bf16 v[12:15], v[134:137], v[196:199], v[12:15]
	v_mfma_f32_16x16x32_bf16 v[60:63], v[126:129], v[204:207], v[60:63]
	v_mfma_f32_16x16x32_bf16 v[4:7], v[134:137], v[204:207], v[4:7]
	v_mfma_f32_16x16x32_bf16 v[90:93], v[126:129], v[212:215], v[90:93]
	v_mfma_f32_16x16x32_bf16 v[28:31], v[134:137], v[212:215], v[28:31]
	v_mfma_f32_16x16x32_bf16 v[74:77], v[146:149], v[162:165], v[74:77]
	v_mfma_f32_16x16x32_bf16 v[16:19], v[154:157], v[162:165], v[16:19]
	v_mfma_f32_16x16x32_bf16 v[66:69], v[146:149], v[192:195], v[66:69]
	v_mfma_f32_16x16x32_bf16 v[8:11], v[154:157], v[192:195], v[8:11]
	v_mfma_f32_16x16x32_bf16 v[56:59], v[146:149], v[200:203], v[56:59]
	v_mfma_f32_16x16x32_bf16 v[0:3], v[154:157], v[200:203], v[0:3]
	v_mfma_f32_16x16x32_bf16 v[86:89], v[146:149], v[208:211], v[86:89]
	v_mfma_f32_16x16x32_bf16 v[24:27], v[154:157], v[208:211], v[24:27]
	v_mfma_f32_16x16x32_bf16 v[74:77], v[150:153], v[166:169], v[74:77]
	v_mfma_f32_16x16x32_bf16 v[16:19], v[158:161], v[166:169], v[16:19]
	v_mfma_f32_16x16x32_bf16 v[66:69], v[150:153], v[196:199], v[66:69]
	v_mfma_f32_16x16x32_bf16 v[8:11], v[158:161], v[196:199], v[8:11]
	v_mfma_f32_16x16x32_bf16 v[56:59], v[150:153], v[204:207], v[56:59]
	v_mfma_f32_16x16x32_bf16 v[0:3], v[158:161], v[204:207], v[0:3]
	v_mfma_f32_16x16x32_bf16 v[86:89], v[150:153], v[212:215], v[86:89]
	v_mfma_f32_16x16x32_bf16 v[24:27], v[158:161], v[212:215], v[24:27]
	s_setprio 0
	s_barrier
; #define PG8_STAGE(bufoff, gbase, voff) do { _Pragma("unroll") for (int _i = 0; _i < 2; ++_i) \
;         __builtin_amdgcn_global_load_lds((const unsigned*)((const char*)(gbase) + (voff)[_i]), (PG8_LAS unsigned*)(lds + (bufoff) + ldsw + _i * 8192), 16, 0, 0); } while (0)
; #define PG8_LDA(dst, b, h) do { _Pragma("unroll") for (int m = 0; m < 4; ++m) _Pragma("unroll") for (int k = 0; k < 2; ++k) dst[m][k] = *(const PG8_LAS bf16x8*)(lds + PG8_SA(b, h) + aoff + m * 2048 + k * 1024); } while (0)
; #define PG8_LDB(dst, b, h) do { _Pragma("unroll") for (int n = 0; n < 2; ++n) _Pragma("unroll") for (int k = 0; k < 2; ++k) dst[n][k] = *(const PG8_LAS bf16x8*)(lds + PG8_SB(b, h) + boff + n * 2048 + k * 1024); } while (0)
; #define PG8_MMA(ai, bj, At, Bt) do { __builtin_amdgcn_s_setprio(1); _Pragma("unroll") for (int m = 0; m < 4; ++m) _Pragma("unroll") for (int n = 0; n < 2; ++n) _Pragma("unroll") for (int k = 0; k < 2; ++k) \
;         acc[ai][bj][m][n] = __builtin_amdgcn_mfma_f32_16x16x32_bf16(Bt[n][k], At[m][k], acc[ai][bj][m][n], 0, 0, 0); __builtin_amdgcn_s_setprio(0); } while (0)
; #define PG8_WAIT_V(n) asm volatile("s_waitcnt vmcnt(" #n ")" ::: "memory")
; #define PG8_WAIT_L(n) asm volatile("s_waitcnt lgkmcnt(" #n ")" ::: "memory")
; #define PG8_BAR __builtin_amdgcn_s_barrier()
; #define PG8_SCHED __builtin_amdgcn_sched_barrier(0)
; template <class Epi, class Sched, bool ALIGN_EPI = false, bool SP2 = false>
; __device__ __forceinline__ void gemm_phase(PG8_LAS unsigned char* lds, const Gemm g, const Sched& S, const Epi& E, int tid_in) {
;     ...
;             PG8_LDB(B0, 1, 0); PG8_LDB(B1, 1, 1); PG8_SCHED; PG8_LDA(At, 1, 0); PG8_STAGE(PG8_SA(0, 1), a2 + hstep, voffA);
;             PG8_WAIT_V(8); PG8_WAIT_L(0); PG8_BAR; PG8_MMA(0, 0, At, B0); PG8_MMA(0, 1, At, B1); PG8_BAR; PG8_SCHED;
;             PG8_LDA(At, 1, 1); PG8_STAGE(PG8_SB(1, 0), b3, voffB); PG8_STAGE(PG8_SB(1, 1), b3 + hstep, voffB); PG8_STAGE(PG8_SA(1, 0), a3, voffA);
;             PG8_WAIT_V(8); PG8_WAIT_L(0); PG8_BAR; PG8_MMA(1, 0, At, B0); PG8_MMA(1, 1, At, B1); PG8_BAR; PG8_SCHED;
	s_add_i32 s45, 0, 0x18000
	v_add_u32_e32 v64, s45, v171
	s_add_i32 s46, 0, 0x1c000
	ds_read_b128 v[122:125], v64
	ds_read_b128 v[126:129], v64 offset:1024
	ds_read_b128 v[130:133], v64 offset:2048
	ds_read_b128 v[134:137], v64 offset:3072
	v_add_u32_e32 v64, s46, v171
	ds_read_b128 v[146:149], v64
	ds_read_b128 v[150:153], v64 offset:1024
	ds_read_b128 v[154:157], v64 offset:2048
	ds_read_b128 v[158:161], v64 offset:3072
	s_add_u32 s30, s30, 0x40000
	s_addc_u32 s31, s31, 0
	s_mov_b32 m0, s79
	ds_read_b128 v[162:165], v216 offset:32768
	ds_read_b128 v[166:169], v216 offset:33792
	ds_read_b128 v[192:195], v216 offset:34816
	ds_read_b128 v[196:199], v216 offset:35840
	ds_read_b128 v[200:203], v216 offset:36864
	ds_read_b128 v[204:207], v216 offset:37888
	ds_read_b128 v[208:211], v216 offset:38912
	ds_read_b128 v[212:215], v216 offset:39936
	global_load_lds_dwordx4 v176, s[30:31]
	s_mov_b32 m0, s82
	s_nop 0
	global_load_lds_dwordx4 v180, s[30:31]
	s_waitcnt vmcnt(8)
	s_waitcnt lgkmcnt(0)
	s_barrier
	s_setprio 1
	s_waitcnt lgkmcnt(0)
	v_mfma_f32_16x16x32_bf16 v[114:117], v[122:125], v[162:165], v[114:117]
	v_mfma_f32_16x16x32_bf16 v[106:109], v[130:133], v[162:165], v[106:109]
	v_mfma_f32_16x16x32_bf16 v[142:145], v[122:125], v[192:195], v[142:145]
	v_mfma_f32_16x16x32_bf16 v[44:47], v[130:133], v[192:195], v[44:47]
	v_mfma_f32_16x16x32_bf16 v[110:113], v[122:125], v[200:203], v[110:113]
	v_mfma_f32_16x16x32_bf16 v[36:39], v[130:133], v[200:203], v[36:39]
	v_mfma_f32_16x16x32_bf16 v[118:121], v[122:125], v[208:211], v[118:121]
	v_mfma_f32_16x16x32_bf16 v[52:55], v[130:133], v[208:211], v[52:55]
	v_mfma_f32_16x16x32_bf16 v[114:117], v[126:129], v[166:169], v[114:117]
	v_mfma_f32_16x16x32_bf16 v[106:109], v[134:137], v[166:169], v[106:109]
	v_mfma_f32_16x16x32_bf16 v[142:145], v[126:129], v[196:199], v[142:145]
	v_mfma_f32_16x16x32_bf16 v[44:47], v[134:137], v[196:199], v[44:47]
	v_mfma_f32_16x16x32_bf16 v[110:113], v[126:129], v[204:207], v[110:113]
	v_mfma_f32_16x16x32_bf16 v[36:39], v[134:137], v[204:207], v[36:39]
	v_mfma_f32_16x16x32_bf16 v[118:121], v[126:129], v[212:215], v[118:121]
	v_mfma_f32_16x16x32_bf16 v[52:55], v[134:137], v[212:215], v[52:55]
	v_mfma_f32_16x16x32_bf16 v[102:105], v[146:149], v[162:165], v[102:105]
	v_mfma_f32_16x16x32_bf16 v[78:81], v[154:157], v[162:165], v[78:81]
	v_mfma_f32_16x16x32_bf16 v[138:141], v[146:149], v[192:195], v[138:141]
	v_mfma_f32_16x16x32_bf16 v[40:43], v[154:157], v[192:195], v[40:43]
	v_mfma_f32_16x16x32_bf16 v[98:101], v[146:149], v[200:203], v[98:101]
	v_mfma_f32_16x16x32_bf16 v[32:35], v[154:157], v[200:203], v[32:35]
	v_mfma_f32_16x16x32_bf16 v[94:97], v[146:149], v[208:211], v[94:97]
	v_mfma_f32_16x16x32_bf16 v[48:51], v[154:157], v[208:211], v[48:51]
	v_mfma_f32_16x16x32_bf16 v[102:105], v[150:153], v[166:169], v[102:105]
	v_mfma_f32_16x16x32_bf16 v[78:81], v[158:161], v[166:169], v[78:81]
	v_mfma_f32_16x16x32_bf16 v[138:141], v[150:153], v[196:199], v[138:141]
	v_mfma_f32_16x16x32_bf16 v[40:43], v[158:161], v[196:199], v[40:43]
	v_mfma_f32_16x16x32_bf16 v[98:101], v[150:153], v[204:207], v[98:101]
	v_mfma_f32_16x16x32_bf16 v[32:35], v[158:161], v[204:207], v[32:35]
	v_mfma_f32_16x16x32_bf16 v[94:97], v[150:153], v[212:215], v[94:97]
	v_mfma_f32_16x16x32_bf16 v[48:51], v[158:161], v[212:215], v[48:51]
	s_setprio 0
	s_barrier
	s_add_i32 s30, s45, s9
	s_mov_b32 m0, s30
	ds_read_b128 v[162:165], v216 offset:49152
	ds_read_b128 v[166:169], v216 offset:50176
	ds_read_b128 v[192:195], v216 offset:51200
	ds_read_b128 v[196:199], v216 offset:52224
	ds_read_b128 v[200:203], v216 offset:53248
	ds_read_b128 v[204:207], v216 offset:54272
	ds_read_b128 v[208:211], v216 offset:55296
	ds_read_b128 v[212:215], v216 offset:56320
	s_add_u32 s98, s28, 0x80
	s_addc_u32 s99, s29, 0
	global_load_lds_dwordx4 v178, s[98:99]
	s_add_i32 m0, s30, 0x2000
	s_add_u32 s28, s28, 0x40080
	v_lshl_add_u64 v[172:173], v[220:221], 0, s[92:93]
	s_addc_u32 s29, s29, 0
	s_add_i32 s30, s46, s9
	global_load_lds_dwordx4 v[172:173], off
	s_mov_b32 m0, s30
	s_nop 0
	global_load_lds_dwordx4 v178, s[28:29]
	s_add_i32 m0, s30, 0x2000
	s_nop 0
	global_load_lds_dwordx4 v182, s[28:29]
	v_lshl_add_u64 v[172:173], v[222:223], 0, s[92:93]
	s_mov_b32 m0, s85
	s_nop 0
	global_load_lds_dwordx4 v[172:173], off
	v_lshl_add_u64 v[172:173], v[224:225], 0, s[92:93]
	s_mov_b32 m0, s8
	s_nop 0
	global_load_lds_dwordx4 v[172:173], off
	s_waitcnt vmcnt(8)
	s_waitcnt lgkmcnt(0)
	s_barrier
	s_setprio 1
	s_waitcnt lgkmcnt(0)
	v_mfma_f32_16x16x32_bf16 v[82:85], v[122:125], v[162:165], v[82:85]
	v_mfma_f32_16x16x32_bf16 v[20:23], v[130:133], v[162:165], v[20:23]
	v_mfma_f32_16x16x32_bf16 v[70:73], v[122:125], v[192:195], v[70:73]
	v_mfma_f32_16x16x32_bf16 v[12:15], v[130:133], v[192:195], v[12:15]
	v_mfma_f32_16x16x32_bf16 v[60:63], v[122:125], v[200:203], v[60:63]
	v_mfma_f32_16x16x32_bf16 v[4:7], v[130:133], v[200:203], v[4:7]
	v_mfma_f32_16x16x32_bf16 v[90:93], v[122:125], v[208:211], v[90:93]
	v_mfma_f32_16x16x32_bf16 v[28:31], v[130:133], v[208:211], v[28:31]
	v_mfma_f32_16x16x32_bf16 v[82:85], v[126:129], v[166:169], v[82:85]
	v_mfma_f32_16x16x32_bf16 v[20:23], v[134:137], v[166:169], v[20:23]
	v_mfma_f32_16x16x32_bf16 v[70:73], v[126:129], v[196:199], v[70:73]
	v_mfma_f32_16x16x32_bf16 v[12:15], v[134:137], v[196:199], v[12:15]
	v_mfma_f32_16x16x32_bf16 v[60:63], v[126:129], v[204:207], v[60:63]
	v_mfma_f32_16x16x32_bf16 v[4:7], v[134:137], v[204:207], v[4:7]
	v_mfma_f32_16x16x32_bf16 v[90:93], v[126:129], v[212:215], v[90:93]
	v_mfma_f32_16x16x32_bf16 v[28:31], v[134:137], v[212:215], v[28:31]
	v_mfma_f32_16x16x32_bf16 v[74:77], v[146:149], v[162:165], v[74:77]
	v_mfma_f32_16x16x32_bf16 v[16:19], v[154:157], v[162:165], v[16:19]
	v_mfma_f32_16x16x32_bf16 v[66:69], v[146:149], v[192:195], v[66:69]
	v_mfma_f32_16x16x32_bf16 v[8:11], v[154:157], v[192:195], v[8:11]
	v_mfma_f32_16x16x32_bf16 v[56:59], v[146:149], v[200:203], v[56:59]
	v_mfma_f32_16x16x32_bf16 v[0:3], v[154:157], v[200:203], v[0:3]
	v_mfma_f32_16x16x32_bf16 v[86:89], v[146:149], v[208:211], v[86:89]
	v_mfma_f32_16x16x32_bf16 v[24:27], v[154:157], v[208:211], v[24:27]
	v_mfma_f32_16x16x32_bf16 v[74:77], v[150:153], v[166:169], v[74:77]
	v_mfma_f32_16x16x32_bf16 v[16:19], v[158:161], v[166:169], v[16:19]
	v_mfma_f32_16x16x32_bf16 v[66:69], v[150:153], v[196:199], v[66:69]
	v_mfma_f32_16x16x32_bf16 v[8:11], v[158:161], v[196:199], v[8:11]
	v_mfma_f32_16x16x32_bf16 v[56:59], v[150:153], v[204:207], v[56:59]
	v_mfma_f32_16x16x32_bf16 v[0:3], v[158:161], v[204:207], v[0:3]
	v_mfma_f32_16x16x32_bf16 v[86:89], v[150:153], v[212:215], v[86:89]
	v_mfma_f32_16x16x32_bf16 v[24:27], v[158:161], v[212:215], v[24:27]
	s_setprio 0
	s_barrier
	s_add_i32 s44, s44, 2
	s_add_u32 s26, s26, 0x100
	s_addc_u32 s27, s27, 0
	s_add_u32 s42, s42, 0x100
	s_addc_u32 s43, s43, 0
	s_cmp_gt_u32 s44, 13
	s_cbranch_scc0 .LBB0_242

;     DI void run(const float (&part)[2][4], const pg8::Unit& u, int wr, int wc, int fr, int fq, int wid, int lane, LAS float* S, volatile LAS unsigned* flag) const {
;     ...
;         if (lane == 0) __hip_atomic_fetch_add(cnt + 64 * u.pm, 1u, __ATOMIC_RELAXED, __HIP_MEMORY_SCOPE_AGENT);
;         if (wid == 0) {
;             unsigned sp = 0;
;             for (;;) {
;                 if ((unsigned)__builtin_amdgcn_readfirstlane(__hip_atomic_load(cnt + 64 * u.pm, __ATOMIC_RELAXED, __HIP_MEMORY_SCOPE_AGENT)) >= 32u) break;
;                 __builtin_amdgcn_s_sleep(2);
;                 if (++sp > (1u << 20)) { if (lane == 0) __hip_atomic_store(tmo, 1u, __ATOMIC_RELAXED, __HIP_MEMORY_SCOPE_AGENT); break; }
;             }
.LBB0_408:
	s_or_b64 exec, exec, s[24:25]
	s_andn2_b64 vcc, exec, s[48:49]
	s_cbranch_vccnz .LBB0_418
	s_lshl_b32 s24, s22, 6
	s_ashr_i32 s25, s24, 31
	s_lshl_b64 s[24:25], s[24:25], 2
	s_add_u32 s24, s8, s24
	s_addc_u32 s25, s21, s25
	s_mov_b32 s8, 0x100001
	buffer_inv sc1
	s_branch .LBB0_411

;     DI void run(const float (&part)[2][4], const pg8::Unit& u, int wr, int wc, int fr, int fq, int wid, int lane, LAS float* S, volatile LAS unsigned* flag) const {
;     ...
;             __builtin_amdgcn_fence(__ATOMIC_ACQUIRE, "agent");
;         }
;         asm volatile("s_waitcnt vmcnt(0) lgkmcnt(0)" ::: "memory"); __builtin_amdgcn_s_barrier(); asm volatile("" ::: "memory");
;         int ln = lane; asm volatile("" : "+v"(ln));
;         if (ln < 32) {
;             const int r = wid * 32 + ln;
;             const unsigned* sl = (const unsigned*)slots + (size_t)(u.pm * 256 + r) * 16;
;             float v[16];
;             if (local) {
;                 const v4f q0 = ((const v4f*)sl)[0], q1 = ((const v4f*)sl)[1], q2 = ((const v4f*)sl)[2], q3 = ((const v4f*)sl)[3];
; #pragma unroll
;                 for (int k = 0; k < 4; ++k) { v[k] = q0[k]; v[4 + k] = q1[k]; v[8 + k] = q2[k]; v[12 + k] = q3[k]; }
;             } else {
; #pragma unroll
;                 for (int k = 0; k < 16; ++k) v[k] = __uint_as_float(__hip_atomic_load(sl + k, __ATOMIC_RELAXED, __HIP_MEMORY_SCOPE_AGENT));
.LBB0_417:
	s_waitcnt vmcnt(0) lgkmcnt(0)
.LBB0_418:
	s_waitcnt vmcnt(0) lgkmcnt(0)
	s_barrier
	v_mov_b32_e32 v0, v163
	s_nop 0
	v_cmp_lt_i32_e32 vcc, 31, v0
	s_and_saveexec_b64 s[24:25], vcc
	s_xor_b64 s[24:25], exec, s[24:25]
	s_lshl_b32 s8, s22, 8
	s_or_saveexec_b64 s[24:25], s[24:25]
	s_waitcnt lgkmcnt(0)
	v_mov_b32_e32 v150, s8
	s_xor_b64 exec, exec, s[24:25]
	s_cbranch_execz .LBB0_426
	v_add_u32_e32 v64, s84, v0
	s_lshl_b32 s8, s22, 8
	v_add_u32_e32 v0, s8, v64
	v_ashrrev_i32_e32 v1, 31, v0
	v_lshlrev_b64 v[0:1], 6, v[0:1]
	v_lshl_add_u64 v[158:159], s[30:31], 0, v[0:1]
	s_andn2_b64 vcc, exec, s[52:53]
	s_mov_b64 s[22:23], -1
	s_cbranch_vccnz .LBB0_423
	global_load_dword v4, v[158:159], off sc1
	global_load_dword v156, v[158:159], off offset:4 sc1
	global_load_dword v6, v[158:159], off offset:8 sc1
	global_load_dword v154, v[158:159], off offset:12 sc1
	global_load_dword v0, v[158:159], off offset:16 sc1
	global_load_dword v152, v[158:159], off offset:20 sc1
	global_load_dword v2, v[158:159], off offset:24 sc1
	global_load_dword v150, v[158:159], off offset:28 sc1
	global_load_dword v5, v[158:159], off offset:32 sc1
	global_load_dword v157, v[158:159], off offset:36 sc1
	global_load_dword v7, v[158:159], off offset:40 sc1
	global_load_dword v155, v[158:159], off offset:44 sc1
	global_load_dword v1, v[158:159], off offset:48 sc1
	global_load_dword v153, v[158:159], off offset:52 sc1
	global_load_dword v3, v[158:159], off offset:56 sc1
	global_load_dword v151, v[158:159], off offset:60 sc1
	s_mov_b64 s[22:23], 0

; #define PG8_STAGE(bufoff, gbase, voff) do { _Pragma("unroll") for (int _i = 0; _i < 2; ++_i) \
;         __builtin_amdgcn_global_load_lds((const unsigned*)((const char*)(gbase) + (voff)[_i]), (PG8_LAS unsigned*)(lds + (bufoff) + ldsw + _i * 8192), 16, 0, 0); } while (0)
; #define PG8_LDA(dst, b, h) do { _Pragma("unroll") for (int m = 0; m < 4; ++m) _Pragma("unroll") for (int k = 0; k < 2; ++k) dst[m][k] = *(const PG8_LAS bf16x8*)(lds + PG8_SA(b, h) + aoff + m * 2048 + k * 1024); } while (0)
; #define PG8_LDB(dst, b, h) do { _Pragma("unroll") for (int n = 0; n < 2; ++n) _Pragma("unroll") for (int k = 0; k < 2; ++k) dst[n][k] = *(const PG8_LAS bf16x8*)(lds + PG8_SB(b, h) + boff + n * 2048 + k * 1024); } while (0)
; template <class Epi, class Sched, bool ALIGN_EPI = false, bool SP2 = false>
; __device__ __forceinline__ void gemm_phase(PG8_LAS unsigned char* lds, const Gemm g, const Sched& S, const Epi& E, int tid_in) {
;     ...
;         const bool has_next = S.next(ui + 1, nxt);
;         const char* nA = has_next ? g.apanel(nxt.pm, tstep) : cA; const char* nB = has_next ? (const char*)g.Bt + (size_t)nxt.pn * tstep : cB;
;         for (int seg = 0; seg < (Epi::KSEG ? 3 : 1); ++seg) {
;         if constexpr (Epi::KSEG) { if (seg > 0) E.kscale(acc, seg, cur, wr, fr); }
;         const int tb_ = Epi::KSEG ? (seg == 0 ? 0 : (seg == 1 ? 8 : 12)) : 0, te_ = Epi::KSEG ? (seg == 0 ? 8 : (seg == 1 ? 12 : nt)) : nt;
; #pragma unroll 1
;         for (int t = tb_; t < te_; t += 2) {
;             const bool last = (t == nt - 2);
;             const char* a1 = cA + (size_t)(t + 1) * kstep;
;             const char* a2 = last ? nA : cA + (size_t)(t + 2) * kstep; const char* b2 = last ? nB : cB + (size_t)(t + 2) * kstep;
;             const char* a3 = a2 + kstep; const char* b3 = b2 + kstep;
;             if (last && has_next) S.a_ready(nxt);
;             if constexpr (SP2) {
;             PG8_LDB(B0, 0, 0); PG8_LDB(B1, 0, 1); PG8_SCHED; PG8_LDA(At, 0, 0); PG8_STAGE(PG8_SA(1, 1), a1 + hstep, voffA);
;             PG8_WAIT_V(8); PG8_WAIT_L(0); PG8_BAR; PG8_MMA(0, 0, At, B0); PG8_MMA(0, 1, At, B1); PG8_BAR; PG8_SCHED;
;     DI void operator()(const pg8::f32x4 (&acc)[2][2][4][2], const pg8::Unit& u, int wr, int wc, int fr, int fq) const {
;     ...
;                 const int row = u.pm * 256 + ai * 128 + wr * 64 + m * 16 + fr; const float rs = rstdx[row];
.LBB0_753:
	s_ashr_i32 s19, s18, 31
	s_lshl_b64 s[20:21], s[18:19], 19
	s_add_u32 s20, s7, s20
	s_addc_u32 s21, s34, s21
	s_and_b64 s[22:23], s[38:39], exec
	s_cselect_b32 s19, s21, s27
	s_cselect_b32 s44, s20, s26
	s_ashr_i32 s17, s16, 31
	s_lshl_b64 s[22:23], s[16:17], 19
	v_readlane_b32 s30, v255, 3
	v_readlane_b32 s31, v255, 4
	s_add_u32 s22, s30, s22
	s_addc_u32 s23, s31, s23
	s_and_b64 s[30:31], s[38:39], exec
	s_cselect_b32 s17, s23, s29
	s_cselect_b32 s45, s22, s28
	s_add_u32 s26, s26, 0x40080
	s_addc_u32 s27, s27, 0
	s_add_u32 s46, s28, 0x100
	s_addc_u32 s47, s29, 0
	s_mov_b32 s48, -2
	s_waitcnt vmcnt(0)
	s_lshl_b32 s100, s24, 8
	v_add_u32_e32 v173, s100, v144
	v_mov_b32_e32 v250, v173
	v_ashrrev_i32_e32 v251, 31, v250
	v_lshl_add_u64 v[250:251], v[250:251], 2, s[8:9]
	global_load_dword v174, v[250:251], off
	v_add_u32_e32 v232, s100, v146
	v_ashrrev_i32_e32 v233, 31, v232
	v_lshl_add_u64 v[232:233], v[232:233], 2, s[8:9]
	global_load_dword v232, v[232:233], off
	v_add_u32_e32 v238, s100, v147
	v_ashrrev_i32_e32 v239, 31, v238
	v_lshl_add_u64 v[238:239], v[238:239], 2, s[8:9]
	global_load_dword v238, v[238:239], off
	v_add_u32_e32 v242, s100, v148
	v_ashrrev_i32_e32 v243, 31, v242
	v_lshl_add_u64 v[242:243], v[242:243], 2, s[8:9]
	global_load_dword v242, v[242:243], off
	v_add_u32_e32 v244, 0x80, v173
	v_ashrrev_i32_e32 v245, 31, v244
	v_lshl_add_u64 v[244:245], v[244:245], 2, s[8:9]
	global_load_dword v244, v[244:245], off
	v_add_u32_e32 v246, 0x90, v173
	v_ashrrev_i32_e32 v247, 31, v246
	v_lshl_add_u64 v[246:247], v[246:247], 2, s[8:9]
	global_load_dword v246, v[246:247], off
	v_add_u32_e32 v248, 0xa0, v173
	v_ashrrev_i32_e32 v249, 31, v248
	v_lshl_add_u64 v[248:249], v[248:249], 2, s[8:9]
	global_load_dword v248, v[248:249], off
	v_add_u32_e32 v250, 0xb0, v173
	v_ashrrev_i32_e32 v251, 31, v250
	v_lshl_add_u64 v[250:251], v[250:251], 2, s[8:9]
	global_load_dword v250, v[250:251], off
	s_add_u32 s28, s26, 0xfffc0080
	s_addc_u32 s29, s27, -1
	s_add_i32 s49, 0, 0x10000
	s_cmp_eq_u32 s48, 12
	s_cselect_b32 s31, s19, s29
	s_cselect_b32 s30, s44, s28
	v_add_u32_e32 v142, s49, v145
	s_cselect_b32 s29, s17, s47
	s_cselect_b32 s28, s45, s46
	s_add_i32 s52, 0, 0x14000
	ds_read_b128 v[150:153], v142
	ds_read_b128 v[154:157], v142 offset:1024
	ds_read_b128 v[158:161], v142 offset:2048
	ds_read_b128 v[162:165], v142 offset:3072
	v_add_u32_e32 v142, s52, v145
	ds_read_b128 v[166:169], v142
	ds_read_b128 v[176:179], v142 offset:1024
	ds_read_b128 v[180:183], v142 offset:2048
	ds_read_b128 v[184:187], v142 offset:3072
	s_add_i32 m0, s35, 0xc000
	ds_read_b128 v[188:191], v149
	ds_read_b128 v[192:195], v149 offset:1024
	ds_read_b128 v[196:199], v149 offset:2048
	ds_read_b128 v[200:203], v149 offset:3072
	ds_read_b128 v[204:207], v149 offset:4096
	ds_read_b128 v[208:211], v149 offset:5120
	ds_read_b128 v[212:215], v149 offset:6144
	ds_read_b128 v[216:219], v149 offset:7168
	global_load_lds_dwordx4 v138, s[26:27]
	s_add_i32 m0, s35, 0xe000
	s_nop 0
	global_load_lds_dwordx4 v140, s[26:27]
	s_waitcnt vmcnt(8)
	s_waitcnt lgkmcnt(0)
	s_barrier
	s_setprio 1
	s_waitcnt lgkmcnt(0)
	v_mfma_f32_16x16x32_bf16 v[126:129], v[150:153], v[188:191], 0
	v_mfma_f32_16x16x32_bf16 v[122:125], v[158:161], v[188:191], 0
	v_mfma_f32_16x16x32_bf16 v[110:113], v[150:153], v[196:199], 0
	v_mfma_f32_16x16x32_bf16 v[106:109], v[158:161], v[196:199], 0
	v_mfma_f32_16x16x32_bf16 v[94:97], v[150:153], v[204:207], 0
	v_mfma_f32_16x16x32_bf16 v[90:93], v[158:161], v[204:207], 0
	v_mfma_f32_16x16x32_bf16 v[78:81], v[150:153], v[212:215], 0
	v_mfma_f32_16x16x32_bf16 v[74:77], v[158:161], v[212:215], 0
	v_mfma_f32_16x16x32_bf16 v[126:129], v[154:157], v[192:195], v[126:129]
	v_mfma_f32_16x16x32_bf16 v[122:125], v[162:165], v[192:195], v[122:125]
	v_mfma_f32_16x16x32_bf16 v[110:113], v[154:157], v[200:203], v[110:113]
	v_mfma_f32_16x16x32_bf16 v[106:109], v[162:165], v[200:203], v[106:109]
	v_mfma_f32_16x16x32_bf16 v[94:97], v[154:157], v[208:211], v[94:97]
	v_mfma_f32_16x16x32_bf16 v[90:93], v[162:165], v[208:211], v[90:93]
	v_mfma_f32_16x16x32_bf16 v[78:81], v[154:157], v[216:219], v[78:81]
	v_mfma_f32_16x16x32_bf16 v[74:77], v[162:165], v[216:219], v[74:77]
	v_mfma_f32_16x16x32_bf16 v[118:121], v[166:169], v[188:191], 0
	v_mfma_f32_16x16x32_bf16 v[114:117], v[180:183], v[188:191], 0
	v_mfma_f32_16x16x32_bf16 v[102:105], v[166:169], v[196:199], 0
	v_mfma_f32_16x16x32_bf16 v[98:101], v[180:183], v[196:199], 0
	v_mfma_f32_16x16x32_bf16 v[86:89], v[166:169], v[204:207], 0
	v_mfma_f32_16x16x32_bf16 v[82:85], v[180:183], v[204:207], 0
	v_mfma_f32_16x16x32_bf16 v[70:73], v[166:169], v[212:215], 0
	v_mfma_f32_16x16x32_bf16 v[66:69], v[180:183], v[212:215], 0
	v_mfma_f32_16x16x32_bf16 v[118:121], v[176:179], v[192:195], v[118:121]
	v_mfma_f32_16x16x32_bf16 v[114:117], v[184:187], v[192:195], v[114:117]
	v_mfma_f32_16x16x32_bf16 v[102:105], v[176:179], v[200:203], v[102:105]
	v_mfma_f32_16x16x32_bf16 v[98:101], v[184:187], v[200:203], v[98:101]
	v_mfma_f32_16x16x32_bf16 v[86:89], v[176:179], v[208:211], v[86:89]
	v_mfma_f32_16x16x32_bf16 v[82:85], v[184:187], v[208:211], v[82:85]
	v_mfma_f32_16x16x32_bf16 v[70:73], v[176:179], v[216:219], v[70:73]
	v_mfma_f32_16x16x32_bf16 v[66:69], v[184:187], v[216:219], v[66:69]
	s_setprio 0
	s_barrier
; #define PG8_STAGE(bufoff, gbase, voff) do { _Pragma("unroll") for (int _i = 0; _i < 2; ++_i) \
;         __builtin_amdgcn_global_load_lds((const unsigned*)((const char*)(gbase) + (voff)[_i]), (PG8_LAS unsigned*)(lds + (bufoff) + ldsw + _i * 8192), 16, 0, 0); } while (0)
; #define PG8_LDA(dst, b, h) do { _Pragma("unroll") for (int m = 0; m < 4; ++m) _Pragma("unroll") for (int k = 0; k < 2; ++k) dst[m][k] = *(const PG8_LAS bf16x8*)(lds + PG8_SA(b, h) + aoff + m * 2048 + k * 1024); } while (0)
; #define PG8_LDB(dst, b, h) do { _Pragma("unroll") for (int n = 0; n < 2; ++n) _Pragma("unroll") for (int k = 0; k < 2; ++k) dst[n][k] = *(const PG8_LAS bf16x8*)(lds + PG8_SB(b, h) + boff + n * 2048 + k * 1024); } while (0)
; #define PG8_MMA(ai, bj, At, Bt) do { __builtin_amdgcn_s_setprio(1); _Pragma("unroll") for (int m = 0; m < 4; ++m) _Pragma("unroll") for (int n = 0; n < 2; ++n) _Pragma("unroll") for (int k = 0; k < 2; ++k) \
;         acc[ai][bj][m][n] = __builtin_amdgcn_mfma_f32_16x16x32_bf16(Bt[n][k], At[m][k], acc[ai][bj][m][n], 0, 0, 0); __builtin_amdgcn_s_setprio(0); } while (0)
; #define PG8_WAIT_V(n) asm volatile("s_waitcnt vmcnt(" #n ")" ::: "memory")
; #define PG8_WAIT_L(n) asm volatile("s_waitcnt lgkmcnt(" #n ")" ::: "memory")
; #define PG8_BAR __builtin_amdgcn_s_barrier()
; #define PG8_SCHED __builtin_amdgcn_sched_barrier(0)
; template <class Epi, class Sched, bool ALIGN_EPI = false, bool SP2 = false>
; __device__ __forceinline__ void gemm_phase(PG8_LAS unsigned char* lds, const Gemm g, const Sched& S, const Epi& E, int tid_in) {
;     ...
;             PG8_LDA(At, 0, 1); PG8_STAGE(PG8_SB(0, 0), b2, voffB); PG8_STAGE(PG8_SB(0, 1), b2 + hstep, voffB); PG8_STAGE(PG8_SA(0, 0), a2, voffA);
;             PG8_WAIT_V(8); PG8_WAIT_L(0); PG8_BAR; PG8_MMA(1, 0, At, B0); PG8_MMA(1, 1, At, B1); PG8_BAR; PG8_SCHED;
;             PG8_LDB(B0, 1, 0); PG8_LDB(B1, 1, 1); PG8_SCHED; PG8_LDA(At, 1, 0); PG8_STAGE(PG8_SA(0, 1), a2 + hstep, voffA);
;             PG8_WAIT_V(8); PG8_WAIT_L(0); PG8_BAR; PG8_MMA(0, 0, At, B0); PG8_MMA(0, 1, At, B1); PG8_BAR; PG8_SCHED;
	s_add_i32 s49, s49, s6
	v_lshl_add_u64 v[142:143], s[28:29], 0, v[132:133]
	s_mov_b32 m0, s49
	ds_read_b128 v[188:191], v149 offset:16384
	ds_read_b128 v[192:195], v149 offset:17408
	ds_read_b128 v[196:199], v149 offset:18432
	ds_read_b128 v[200:203], v149 offset:19456
	ds_read_b128 v[204:207], v149 offset:20480
	ds_read_b128 v[208:211], v149 offset:21504
	ds_read_b128 v[212:215], v149 offset:22528
	ds_read_b128 v[216:219], v149 offset:23552
	global_load_lds_dwordx4 v132, s[28:29]
	s_add_i32 m0, s49, 0x2000
	s_add_u32 s50, s28, 0x40000
	v_lshl_add_u64 v[170:171], s[28:29], 0, v[136:137]
	s_addc_u32 s51, s29, 0
	s_add_i32 s49, s52, s6
	global_load_lds_dwordx4 v136, s[28:29]
	s_mov_b32 m0, s49
	v_lshl_add_u64 v[222:223], s[30:31], 0, v[134:135]
	global_load_lds_dwordx4 v132, s[50:51]
	s_add_i32 m0, s49, 0x2000
	s_nop 0
	global_load_lds_dwordx4 v136, s[50:51]
	v_lshl_add_u64 v[220:221], s[30:31], 0, v[130:131]
	s_mov_b32 m0, s35
	s_nop 0
	global_load_lds_dwordx4 v130, s[30:31]
	s_mov_b32 m0, s36
	s_nop 0
	global_load_lds_dwordx4 v134, s[30:31]
	s_waitcnt vmcnt(8)
	s_waitcnt lgkmcnt(0)
	s_barrier
	s_setprio 1
	s_waitcnt lgkmcnt(0)
	v_mfma_f32_16x16x32_bf16 v[60:63], v[150:153], v[188:191], 0
	v_mfma_f32_16x16x32_bf16 v[56:59], v[158:161], v[188:191], 0
	v_mfma_f32_16x16x32_bf16 v[44:47], v[150:153], v[196:199], 0
	v_mfma_f32_16x16x32_bf16 v[40:43], v[158:161], v[196:199], 0
	v_mfma_f32_16x16x32_bf16 v[28:31], v[150:153], v[204:207], 0
	v_mfma_f32_16x16x32_bf16 v[24:27], v[158:161], v[204:207], 0
	v_mfma_f32_16x16x32_bf16 v[12:15], v[150:153], v[212:215], 0
	v_mfma_f32_16x16x32_bf16 v[8:11], v[158:161], v[212:215], 0
	v_mfma_f32_16x16x32_bf16 v[60:63], v[154:157], v[192:195], v[60:63]
	v_mfma_f32_16x16x32_bf16 v[56:59], v[162:165], v[192:195], v[56:59]
	v_mfma_f32_16x16x32_bf16 v[44:47], v[154:157], v[200:203], v[44:47]
	v_mfma_f32_16x16x32_bf16 v[40:43], v[162:165], v[200:203], v[40:43]
	v_mfma_f32_16x16x32_bf16 v[28:31], v[154:157], v[208:211], v[28:31]
	v_mfma_f32_16x16x32_bf16 v[24:27], v[162:165], v[208:211], v[24:27]
	v_mfma_f32_16x16x32_bf16 v[12:15], v[154:157], v[216:219], v[12:15]
	v_mfma_f32_16x16x32_bf16 v[8:11], v[162:165], v[216:219], v[8:11]
	v_mfma_f32_16x16x32_bf16 v[52:55], v[166:169], v[188:191], 0
	v_mfma_f32_16x16x32_bf16 v[48:51], v[180:183], v[188:191], 0
	v_mfma_f32_16x16x32_bf16 v[36:39], v[166:169], v[196:199], 0
	v_mfma_f32_16x16x32_bf16 v[32:35], v[180:183], v[196:199], 0
	v_mfma_f32_16x16x32_bf16 v[20:23], v[166:169], v[204:207], 0
	v_mfma_f32_16x16x32_bf16 v[16:19], v[180:183], v[204:207], 0
	v_mfma_f32_16x16x32_bf16 v[4:7], v[166:169], v[212:215], 0
	v_mfma_f32_16x16x32_bf16 v[0:3], v[180:183], v[212:215], 0
	v_mfma_f32_16x16x32_bf16 v[52:55], v[176:179], v[192:195], v[52:55]
	v_mfma_f32_16x16x32_bf16 v[48:51], v[184:187], v[192:195], v[48:51]
	v_mfma_f32_16x16x32_bf16 v[36:39], v[176:179], v[200:203], v[36:39]
	v_mfma_f32_16x16x32_bf16 v[32:35], v[184:187], v[200:203], v[32:35]
	v_mfma_f32_16x16x32_bf16 v[20:23], v[176:179], v[208:211], v[20:23]
	v_mfma_f32_16x16x32_bf16 v[16:19], v[184:187], v[208:211], v[16:19]
	v_mfma_f32_16x16x32_bf16 v[4:7], v[176:179], v[216:219], v[4:7]
	v_mfma_f32_16x16x32_bf16 v[0:3], v[184:187], v[216:219], v[0:3]
	s_setprio 0
	s_barrier
	s_add_i32 s49, 0, 0x18000
	s_add_i32 s50, 0, 0x1c000
	v_add_u32_e32 v162, s49, v145
	v_add_u32_e32 v172, s50, v145
	ds_read_b128 v[150:153], v162
	ds_read_b128 v[154:157], v162 offset:1024
	ds_read_b128 v[158:161], v162 offset:2048
	ds_read_b128 v[162:165], v162 offset:3072
	ds_read_b128 v[166:169], v172
	ds_read_b128 v[176:179], v172 offset:1024
	ds_read_b128 v[180:183], v172 offset:2048
	ds_read_b128 v[184:187], v172 offset:3072
	s_add_u32 s30, s30, 0x40000
	s_addc_u32 s31, s31, 0
	s_mov_b32 m0, s37
	ds_read_b128 v[188:191], v149 offset:32768
	ds_read_b128 v[192:195], v149 offset:33792
	ds_read_b128 v[196:199], v149 offset:34816
	ds_read_b128 v[200:203], v149 offset:35840
	ds_read_b128 v[204:207], v149 offset:36864
	ds_read_b128 v[208:211], v149 offset:37888
	ds_read_b128 v[212:215], v149 offset:38912
	ds_read_b128 v[216:219], v149 offset:39936
	global_load_lds_dwordx4 v130, s[30:31]
	s_mov_b32 m0, s40
	s_nop 0
	global_load_lds_dwordx4 v134, s[30:31]
	s_waitcnt vmcnt(8)
	s_waitcnt lgkmcnt(0)
	s_barrier
	s_setprio 1
	s_waitcnt lgkmcnt(0)
	v_mfma_f32_16x16x32_bf16 v[126:129], v[150:153], v[188:191], v[126:129]
	v_mfma_f32_16x16x32_bf16 v[122:125], v[158:161], v[188:191], v[122:125]
	v_mfma_f32_16x16x32_bf16 v[110:113], v[150:153], v[196:199], v[110:113]
	v_mfma_f32_16x16x32_bf16 v[106:109], v[158:161], v[196:199], v[106:109]
	v_mfma_f32_16x16x32_bf16 v[94:97], v[150:153], v[204:207], v[94:97]
	v_mfma_f32_16x16x32_bf16 v[90:93], v[158:161], v[204:207], v[90:93]
	v_mfma_f32_16x16x32_bf16 v[78:81], v[150:153], v[212:215], v[78:81]
	v_mfma_f32_16x16x32_bf16 v[74:77], v[158:161], v[212:215], v[74:77]
	v_mfma_f32_16x16x32_bf16 v[126:129], v[154:157], v[192:195], v[126:129]
	v_mfma_f32_16x16x32_bf16 v[122:125], v[162:165], v[192:195], v[122:125]
	v_mfma_f32_16x16x32_bf16 v[110:113], v[154:157], v[200:203], v[110:113]
	v_mfma_f32_16x16x32_bf16 v[106:109], v[162:165], v[200:203], v[106:109]
	v_mfma_f32_16x16x32_bf16 v[94:97], v[154:157], v[208:211], v[94:97]
	v_mfma_f32_16x16x32_bf16 v[90:93], v[162:165], v[208:211], v[90:93]
	v_mfma_f32_16x16x32_bf16 v[78:81], v[154:157], v[216:219], v[78:81]
	v_mfma_f32_16x16x32_bf16 v[74:77], v[162:165], v[216:219], v[74:77]
	v_mfma_f32_16x16x32_bf16 v[118:121], v[166:169], v[188:191], v[118:121]
	v_mfma_f32_16x16x32_bf16 v[114:117], v[180:183], v[188:191], v[114:117]
	v_mfma_f32_16x16x32_bf16 v[102:105], v[166:169], v[196:199], v[102:105]
	v_mfma_f32_16x16x32_bf16 v[98:101], v[180:183], v[196:199], v[98:101]
	v_mfma_f32_16x16x32_bf16 v[86:89], v[166:169], v[204:207], v[86:89]
	v_mfma_f32_16x16x32_bf16 v[82:85], v[180:183], v[204:207], v[82:85]
	v_mfma_f32_16x16x32_bf16 v[70:73], v[166:169], v[212:215], v[70:73]
	v_mfma_f32_16x16x32_bf16 v[66:69], v[180:183], v[212:215], v[66:69]
	v_mfma_f32_16x16x32_bf16 v[118:121], v[176:179], v[192:195], v[118:121]
	v_mfma_f32_16x16x32_bf16 v[114:117], v[184:187], v[192:195], v[114:117]
	v_mfma_f32_16x16x32_bf16 v[102:105], v[176:179], v[200:203], v[102:105]
	v_mfma_f32_16x16x32_bf16 v[98:101], v[184:187], v[200:203], v[98:101]
	v_mfma_f32_16x16x32_bf16 v[86:89], v[176:179], v[208:211], v[86:89]
	v_mfma_f32_16x16x32_bf16 v[82:85], v[184:187], v[208:211], v[82:85]
	v_mfma_f32_16x16x32_bf16 v[70:73], v[176:179], v[216:219], v[70:73]
	v_mfma_f32_16x16x32_bf16 v[66:69], v[184:187], v[216:219], v[66:69]
	s_setprio 0
	s_barrier
; #define PG8_STAGE(bufoff, gbase, voff) do { _Pragma("unroll") for (int _i = 0; _i < 2; ++_i) \
;         __builtin_amdgcn_global_load_lds((const unsigned*)((const char*)(gbase) + (voff)[_i]), (PG8_LAS unsigned*)(lds + (bufoff) + ldsw + _i * 8192), 16, 0, 0); } while (0)
; #define PG8_LDA(dst, b, h) do { _Pragma("unroll") for (int m = 0; m < 4; ++m) _Pragma("unroll") for (int k = 0; k < 2; ++k) dst[m][k] = *(const PG8_LAS bf16x8*)(lds + PG8_SA(b, h) + aoff + m * 2048 + k * 1024); } while (0)
; #define PG8_LDB(dst, b, h) do { _Pragma("unroll") for (int n = 0; n < 2; ++n) _Pragma("unroll") for (int k = 0; k < 2; ++k) dst[n][k] = *(const PG8_LAS bf16x8*)(lds + PG8_SB(b, h) + boff + n * 2048 + k * 1024); } while (0)
; #define PG8_MMA(ai, bj, At, Bt) do { __builtin_amdgcn_s_setprio(1); _Pragma("unroll") for (int m = 0; m < 4; ++m) _Pragma("unroll") for (int n = 0; n < 2; ++n) _Pragma("unroll") for (int k = 0; k < 2; ++k) \
;         acc[ai][bj][m][n] = __builtin_amdgcn_mfma_f32_16x16x32_bf16(Bt[n][k], At[m][k], acc[ai][bj][m][n], 0, 0, 0); __builtin_amdgcn_s_setprio(0); } while (0)
; #define PG8_WAIT_V(n) asm volatile("s_waitcnt vmcnt(" #n ")" ::: "memory")
; #define PG8_WAIT_L(n) asm volatile("s_waitcnt lgkmcnt(" #n ")" ::: "memory")
; #define PG8_BAR __builtin_amdgcn_s_barrier()
; template <class Epi, class Sched, bool ALIGN_EPI = false, bool SP2 = false>
; __device__ __forceinline__ void gemm_phase(PG8_LAS unsigned char* lds, const Gemm g, const Sched& S, const Epi& E, int tid_in) {
;     ...
;         for (int t = tb_; t < te_; t += 2) {
;             const bool last = (t == nt - 2);
;             const char* a1 = cA + (size_t)(t + 1) * kstep;
;             const char* a2 = last ? nA : cA + (size_t)(t + 2) * kstep; const char* b2 = last ? nB : cB + (size_t)(t + 2) * kstep;
;             const char* a3 = a2 + kstep; const char* b3 = b2 + kstep;
;             if (last && has_next) S.a_ready(nxt);
;             if constexpr (SP2) {
;             PG8_LDB(B0, 0, 0); PG8_LDB(B1, 0, 1); PG8_SCHED; PG8_LDA(At, 0, 0); PG8_STAGE(PG8_SA(1, 1), a1 + hstep, voffA);
;     ...
;             PG8_LDA(At, 1, 1); PG8_STAGE(PG8_SB(1, 0), b3, voffB); PG8_STAGE(PG8_SB(1, 1), b3 + hstep, voffB); PG8_STAGE(PG8_SA(1, 0), a3, voffA);
;             PG8_WAIT_V(8); PG8_WAIT_L(0); PG8_BAR; PG8_MMA(1, 0, At, B0); PG8_MMA(1, 1, At, B1); PG8_BAR; PG8_SCHED;
	s_add_i32 s30, s49, s6
	s_mov_b32 m0, s30
	ds_read_b128 v[188:191], v149 offset:49152
	ds_read_b128 v[192:195], v149 offset:50176
	ds_read_b128 v[196:199], v149 offset:51200
	ds_read_b128 v[200:203], v149 offset:52224
	ds_read_b128 v[204:207], v149 offset:53248
	ds_read_b128 v[208:211], v149 offset:54272
	ds_read_b128 v[212:215], v149 offset:55296
	ds_read_b128 v[216:219], v149 offset:56320
	s_add_u32 s98, s28, 0x80
	s_addc_u32 s99, s29, 0
	global_load_lds_dwordx4 v132, s[98:99]
	s_add_i32 m0, s30, 0x2000
	s_add_u32 s28, s28, 0x40080
	v_lshl_add_u64 v[142:143], v[170:171], 0, s[92:93]
	s_addc_u32 s29, s29, 0
	s_add_i32 s30, s50, s6
	global_load_lds_dwordx4 v[142:143], off
	s_mov_b32 m0, s30
	s_nop 0
	global_load_lds_dwordx4 v132, s[28:29]
	s_add_i32 m0, s30, 0x2000
	s_nop 0
	global_load_lds_dwordx4 v136, s[28:29]
	v_lshl_add_u64 v[142:143], v[220:221], 0, s[92:93]
	s_mov_b32 m0, s41
	s_nop 0
	global_load_lds_dwordx4 v[142:143], off
	v_lshl_add_u64 v[142:143], v[222:223], 0, s[92:93]
	s_mov_b32 m0, s42
	s_nop 0
	global_load_lds_dwordx4 v[142:143], off
	s_waitcnt vmcnt(8)
	s_waitcnt lgkmcnt(0)
	s_barrier
	s_setprio 1
	s_waitcnt lgkmcnt(0)
	v_mfma_f32_16x16x32_bf16 v[60:63], v[150:153], v[188:191], v[60:63]
	v_mfma_f32_16x16x32_bf16 v[56:59], v[158:161], v[188:191], v[56:59]
	v_mfma_f32_16x16x32_bf16 v[44:47], v[150:153], v[196:199], v[44:47]
	v_mfma_f32_16x16x32_bf16 v[40:43], v[158:161], v[196:199], v[40:43]
	v_mfma_f32_16x16x32_bf16 v[28:31], v[150:153], v[204:207], v[28:31]
	v_mfma_f32_16x16x32_bf16 v[24:27], v[158:161], v[204:207], v[24:27]
	v_mfma_f32_16x16x32_bf16 v[12:15], v[150:153], v[212:215], v[12:15]
	v_mfma_f32_16x16x32_bf16 v[8:11], v[158:161], v[212:215], v[8:11]
	v_mfma_f32_16x16x32_bf16 v[60:63], v[154:157], v[192:195], v[60:63]
	v_mfma_f32_16x16x32_bf16 v[56:59], v[162:165], v[192:195], v[56:59]
	v_mfma_f32_16x16x32_bf16 v[44:47], v[154:157], v[200:203], v[44:47]
	v_mfma_f32_16x16x32_bf16 v[40:43], v[162:165], v[200:203], v[40:43]
	v_mfma_f32_16x16x32_bf16 v[28:31], v[154:157], v[208:211], v[28:31]
	v_mfma_f32_16x16x32_bf16 v[24:27], v[162:165], v[208:211], v[24:27]
	v_mfma_f32_16x16x32_bf16 v[12:15], v[154:157], v[216:219], v[12:15]
	v_mfma_f32_16x16x32_bf16 v[8:11], v[162:165], v[216:219], v[8:11]
	v_mfma_f32_16x16x32_bf16 v[52:55], v[166:169], v[188:191], v[52:55]
	v_mfma_f32_16x16x32_bf16 v[48:51], v[180:183], v[188:191], v[48:51]
	v_mfma_f32_16x16x32_bf16 v[36:39], v[166:169], v[196:199], v[36:39]
	v_mfma_f32_16x16x32_bf16 v[32:35], v[180:183], v[196:199], v[32:35]
	v_mfma_f32_16x16x32_bf16 v[20:23], v[166:169], v[204:207], v[20:23]
	v_mfma_f32_16x16x32_bf16 v[16:19], v[180:183], v[204:207], v[16:19]
	v_mfma_f32_16x16x32_bf16 v[4:7], v[166:169], v[212:215], v[4:7]
	v_mfma_f32_16x16x32_bf16 v[0:3], v[180:183], v[212:215], v[0:3]
	v_mfma_f32_16x16x32_bf16 v[52:55], v[176:179], v[192:195], v[52:55]
	v_mfma_f32_16x16x32_bf16 v[48:51], v[184:187], v[192:195], v[48:51]
	v_mfma_f32_16x16x32_bf16 v[36:39], v[176:179], v[200:203], v[36:39]
	v_mfma_f32_16x16x32_bf16 v[32:35], v[184:187], v[200:203], v[32:35]
	v_mfma_f32_16x16x32_bf16 v[20:23], v[176:179], v[208:211], v[20:23]
	v_mfma_f32_16x16x32_bf16 v[16:19], v[184:187], v[208:211], v[16:19]
	v_mfma_f32_16x16x32_bf16 v[4:7], v[176:179], v[216:219], v[4:7]
	v_mfma_f32_16x16x32_bf16 v[0:3], v[184:187], v[216:219], v[0:3]
	s_setprio 0
	s_barrier
	s_add_i32 s48, s48, 2
	s_add_u32 s26, s26, 0x100
	s_addc_u32 s27, s27, 0
	s_add_u32 s46, s46, 0x100
	s_addc_u32 s47, s47, 0
	s_cmp_gt_u32 s48, 13
	s_cbranch_scc0 .LBB0_754
	s_branch .Lpeel_exit_0
.LBB0_754:
	s_add_u32 s28, s26, 0xfffc0080
	s_addc_u32 s29, s27, -1
	s_add_i32 s49, 0, 0x10000
	s_cmp_eq_u32 s48, 12
	s_cselect_b32 s31, s19, s29
	s_cselect_b32 s30, s44, s28
	v_add_u32_e32 v142, s49, v145
	s_cselect_b32 s29, s17, s47
	s_cselect_b32 s28, s45, s46
	s_add_i32 s52, 0, 0x14000
	ds_read_b128 v[150:153], v142
	ds_read_b128 v[154:157], v142 offset:1024
	ds_read_b128 v[158:161], v142 offset:2048
	ds_read_b128 v[162:165], v142 offset:3072
	v_add_u32_e32 v142, s52, v145
	ds_read_b128 v[166:169], v142
	ds_read_b128 v[176:179], v142 offset:1024
	ds_read_b128 v[180:183], v142 offset:2048
	ds_read_b128 v[184:187], v142 offset:3072
	s_add_i32 m0, s35, 0xc000
	ds_read_b128 v[188:191], v149
	ds_read_b128 v[192:195], v149 offset:1024
	ds_read_b128 v[196:199], v149 offset:2048
	ds_read_b128 v[200:203], v149 offset:3072
	ds_read_b128 v[204:207], v149 offset:4096
	ds_read_b128 v[208:211], v149 offset:5120
	ds_read_b128 v[212:215], v149 offset:6144
	ds_read_b128 v[216:219], v149 offset:7168
	global_load_lds_dwordx4 v138, s[26:27]
	s_add_i32 m0, s35, 0xe000
	s_nop 0
	global_load_lds_dwordx4 v140, s[26:27]
	s_waitcnt vmcnt(8)
	s_waitcnt lgkmcnt(0)
	s_barrier
; #define PG8_STAGE(bufoff, gbase, voff) do { _Pragma("unroll") for (int _i = 0; _i < 2; ++_i) \
;         __builtin_amdgcn_global_load_lds((const unsigned*)((const char*)(gbase) + (voff)[_i]), (PG8_LAS unsigned*)(lds + (bufoff) + ldsw + _i * 8192), 16, 0, 0); } while (0)
; #define PG8_LDA(dst, b, h) do { _Pragma("unroll") for (int m = 0; m < 4; ++m) _Pragma("unroll") for (int k = 0; k < 2; ++k) dst[m][k] = *(const PG8_LAS bf16x8*)(lds + PG8_SA(b, h) + aoff + m * 2048 + k * 1024); } while (0)
; #define PG8_MMA(ai, bj, At, Bt) do { __builtin_amdgcn_s_setprio(1); _Pragma("unroll") for (int m = 0; m < 4; ++m) _Pragma("unroll") for (int n = 0; n < 2; ++n) _Pragma("unroll") for (int k = 0; k < 2; ++k) \
;         acc[ai][bj][m][n] = __builtin_amdgcn_mfma_f32_16x16x32_bf16(Bt[n][k], At[m][k], acc[ai][bj][m][n], 0, 0, 0); __builtin_amdgcn_s_setprio(0); } while (0)
; #define PG8_WAIT_V(n) asm volatile("s_waitcnt vmcnt(" #n ")" ::: "memory")
; #define PG8_WAIT_L(n) asm volatile("s_waitcnt lgkmcnt(" #n ")" ::: "memory")
; #define PG8_BAR __builtin_amdgcn_s_barrier()
; #define PG8_SCHED __builtin_amdgcn_sched_barrier(0)
; template <class Epi, class Sched, bool ALIGN_EPI = false, bool SP2 = false>
; __device__ __forceinline__ void gemm_phase(PG8_LAS unsigned char* lds, const Gemm g, const Sched& S, const Epi& E, int tid_in) {
;     ...
;             PG8_WAIT_V(8); PG8_WAIT_L(0); PG8_BAR; PG8_MMA(0, 0, At, B0); PG8_MMA(0, 1, At, B1); PG8_BAR; PG8_SCHED;
;             PG8_LDA(At, 0, 1); PG8_STAGE(PG8_SB(0, 0), b2, voffB); PG8_STAGE(PG8_SB(0, 1), b2 + hstep, voffB); PG8_STAGE(PG8_SA(0, 0), a2, voffA);
;             PG8_WAIT_V(8); PG8_WAIT_L(0); PG8_BAR; PG8_MMA(1, 0, At, B0); PG8_MMA(1, 1, At, B1); PG8_BAR; PG8_SCHED;
	s_setprio 1
	s_waitcnt lgkmcnt(0)
	v_mfma_f32_16x16x32_bf16 v[126:129], v[150:153], v[188:191], v[126:129]
	v_mfma_f32_16x16x32_bf16 v[122:125], v[158:161], v[188:191], v[122:125]
	v_mfma_f32_16x16x32_bf16 v[110:113], v[150:153], v[196:199], v[110:113]
	v_mfma_f32_16x16x32_bf16 v[106:109], v[158:161], v[196:199], v[106:109]
	v_mfma_f32_16x16x32_bf16 v[94:97], v[150:153], v[204:207], v[94:97]
	v_mfma_f32_16x16x32_bf16 v[90:93], v[158:161], v[204:207], v[90:93]
	v_mfma_f32_16x16x32_bf16 v[78:81], v[150:153], v[212:215], v[78:81]
	v_mfma_f32_16x16x32_bf16 v[74:77], v[158:161], v[212:215], v[74:77]
	v_mfma_f32_16x16x32_bf16 v[126:129], v[154:157], v[192:195], v[126:129]
	v_mfma_f32_16x16x32_bf16 v[122:125], v[162:165], v[192:195], v[122:125]
	v_mfma_f32_16x16x32_bf16 v[110:113], v[154:157], v[200:203], v[110:113]
	v_mfma_f32_16x16x32_bf16 v[106:109], v[162:165], v[200:203], v[106:109]
	v_mfma_f32_16x16x32_bf16 v[94:97], v[154:157], v[208:211], v[94:97]
	v_mfma_f32_16x16x32_bf16 v[90:93], v[162:165], v[208:211], v[90:93]
	v_mfma_f32_16x16x32_bf16 v[78:81], v[154:157], v[216:219], v[78:81]
	v_mfma_f32_16x16x32_bf16 v[74:77], v[162:165], v[216:219], v[74:77]
	v_mfma_f32_16x16x32_bf16 v[118:121], v[166:169], v[188:191], v[118:121]
	v_mfma_f32_16x16x32_bf16 v[114:117], v[180:183], v[188:191], v[114:117]
	v_mfma_f32_16x16x32_bf16 v[102:105], v[166:169], v[196:199], v[102:105]
	v_mfma_f32_16x16x32_bf16 v[98:101], v[180:183], v[196:199], v[98:101]
	v_mfma_f32_16x16x32_bf16 v[86:89], v[166:169], v[204:207], v[86:89]
	v_mfma_f32_16x16x32_bf16 v[82:85], v[180:183], v[204:207], v[82:85]
	v_mfma_f32_16x16x32_bf16 v[70:73], v[166:169], v[212:215], v[70:73]
	v_mfma_f32_16x16x32_bf16 v[66:69], v[180:183], v[212:215], v[66:69]
	v_mfma_f32_16x16x32_bf16 v[118:121], v[176:179], v[192:195], v[118:121]
	v_mfma_f32_16x16x32_bf16 v[114:117], v[184:187], v[192:195], v[114:117]
	v_mfma_f32_16x16x32_bf16 v[102:105], v[176:179], v[200:203], v[102:105]
	v_mfma_f32_16x16x32_bf16 v[98:101], v[184:187], v[200:203], v[98:101]
	v_mfma_f32_16x16x32_bf16 v[86:89], v[176:179], v[208:211], v[86:89]
	v_mfma_f32_16x16x32_bf16 v[82:85], v[184:187], v[208:211], v[82:85]
	v_mfma_f32_16x16x32_bf16 v[70:73], v[176:179], v[216:219], v[70:73]
	v_mfma_f32_16x16x32_bf16 v[66:69], v[184:187], v[216:219], v[66:69]
	s_setprio 0
	s_barrier
	s_add_i32 s49, s49, s6
	v_lshl_add_u64 v[142:143], s[28:29], 0, v[132:133]
	s_mov_b32 m0, s49
	ds_read_b128 v[188:191], v149 offset:16384
	ds_read_b128 v[192:195], v149 offset:17408
	ds_read_b128 v[196:199], v149 offset:18432
	ds_read_b128 v[200:203], v149 offset:19456
	ds_read_b128 v[204:207], v149 offset:20480
	ds_read_b128 v[208:211], v149 offset:21504
	ds_read_b128 v[212:215], v149 offset:22528
	ds_read_b128 v[216:219], v149 offset:23552
	global_load_lds_dwordx4 v132, s[28:29]
	s_add_i32 m0, s49, 0x2000
	s_add_u32 s50, s28, 0x40000
	v_lshl_add_u64 v[170:171], s[28:29], 0, v[136:137]
	s_addc_u32 s51, s29, 0
	s_add_i32 s49, s52, s6
	global_load_lds_dwordx4 v136, s[28:29]
	s_mov_b32 m0, s49
	v_lshl_add_u64 v[222:223], s[30:31], 0, v[134:135]
	global_load_lds_dwordx4 v132, s[50:51]
	s_add_i32 m0, s49, 0x2000
	s_nop 0
	global_load_lds_dwordx4 v136, s[50:51]
	v_lshl_add_u64 v[220:221], s[30:31], 0, v[130:131]
	s_mov_b32 m0, s35
	s_nop 0
	global_load_lds_dwordx4 v130, s[30:31]
	s_mov_b32 m0, s36
	s_nop 0
	global_load_lds_dwordx4 v134, s[30:31]
	s_waitcnt vmcnt(8)
	s_waitcnt lgkmcnt(0)
	s_barrier
	s_setprio 1
	s_waitcnt lgkmcnt(0)
	v_mfma_f32_16x16x32_bf16 v[60:63], v[150:153], v[188:191], v[60:63]
	v_mfma_f32_16x16x32_bf16 v[56:59], v[158:161], v[188:191], v[56:59]
	v_mfma_f32_16x16x32_bf16 v[44:47], v[150:153], v[196:199], v[44:47]
	v_mfma_f32_16x16x32_bf16 v[40:43], v[158:161], v[196:199], v[40:43]
	v_mfma_f32_16x16x32_bf16 v[28:31], v[150:153], v[204:207], v[28:31]
	v_mfma_f32_16x16x32_bf16 v[24:27], v[158:161], v[204:207], v[24:27]
	v_mfma_f32_16x16x32_bf16 v[12:15], v[150:153], v[212:215], v[12:15]
	v_mfma_f32_16x16x32_bf16 v[8:11], v[158:161], v[212:215], v[8:11]
	v_mfma_f32_16x16x32_bf16 v[60:63], v[154:157], v[192:195], v[60:63]
	v_mfma_f32_16x16x32_bf16 v[56:59], v[162:165], v[192:195], v[56:59]
	v_mfma_f32_16x16x32_bf16 v[44:47], v[154:157], v[200:203], v[44:47]
	v_mfma_f32_16x16x32_bf16 v[40:43], v[162:165], v[200:203], v[40:43]
	v_mfma_f32_16x16x32_bf16 v[28:31], v[154:157], v[208:211], v[28:31]
	v_mfma_f32_16x16x32_bf16 v[24:27], v[162:165], v[208:211], v[24:27]
	v_mfma_f32_16x16x32_bf16 v[12:15], v[154:157], v[216:219], v[12:15]
	v_mfma_f32_16x16x32_bf16 v[8:11], v[162:165], v[216:219], v[8:11]
	v_mfma_f32_16x16x32_bf16 v[52:55], v[166:169], v[188:191], v[52:55]
	v_mfma_f32_16x16x32_bf16 v[48:51], v[180:183], v[188:191], v[48:51]
	v_mfma_f32_16x16x32_bf16 v[36:39], v[166:169], v[196:199], v[36:39]
	v_mfma_f32_16x16x32_bf16 v[32:35], v[180:183], v[196:199], v[32:35]
	v_mfma_f32_16x16x32_bf16 v[20:23], v[166:169], v[204:207], v[20:23]
	v_mfma_f32_16x16x32_bf16 v[16:19], v[180:183], v[204:207], v[16:19]
	v_mfma_f32_16x16x32_bf16 v[4:7], v[166:169], v[212:215], v[4:7]
	v_mfma_f32_16x16x32_bf16 v[0:3], v[180:183], v[212:215], v[0:3]
	v_mfma_f32_16x16x32_bf16 v[52:55], v[176:179], v[192:195], v[52:55]
	v_mfma_f32_16x16x32_bf16 v[48:51], v[184:187], v[192:195], v[48:51]
	v_mfma_f32_16x16x32_bf16 v[36:39], v[176:179], v[200:203], v[36:39]
	v_mfma_f32_16x16x32_bf16 v[32:35], v[184:187], v[200:203], v[32:35]
	v_mfma_f32_16x16x32_bf16 v[20:23], v[176:179], v[208:211], v[20:23]
	v_mfma_f32_16x16x32_bf16 v[16:19], v[184:187], v[208:211], v[16:19]
	v_mfma_f32_16x16x32_bf16 v[4:7], v[176:179], v[216:219], v[4:7]
	v_mfma_f32_16x16x32_bf16 v[0:3], v[184:187], v[216:219], v[0:3]
	s_setprio 0
	s_barrier
; #define PG8_STAGE(bufoff, gbase, voff) do { _Pragma("unroll") for (int _i = 0; _i < 2; ++_i) \
;         __builtin_amdgcn_global_load_lds((const unsigned*)((const char*)(gbase) + (voff)[_i]), (PG8_LAS unsigned*)(lds + (bufoff) + ldsw + _i * 8192), 16, 0, 0); } while (0)
; #define PG8_LDA(dst, b, h) do { _Pragma("unroll") for (int m = 0; m < 4; ++m) _Pragma("unroll") for (int k = 0; k < 2; ++k) dst[m][k] = *(const PG8_LAS bf16x8*)(lds + PG8_SA(b, h) + aoff + m * 2048 + k * 1024); } while (0)
; #define PG8_WAIT_V(n) asm volatile("s_waitcnt vmcnt(" #n ")" ::: "memory")
; #define PG8_WAIT_L(n) asm volatile("s_waitcnt lgkmcnt(" #n ")" ::: "memory")
; #define PG8_BAR __builtin_amdgcn_s_barrier()
; template <class Epi, class Sched, bool ALIGN_EPI = false, bool SP2 = false>
; __device__ __forceinline__ void gemm_phase(PG8_LAS unsigned char* lds, const Gemm g, const Sched& S, const Epi& E, int tid_in) {
;     ...
;         for (int t = tb_; t < te_; t += 2) {
;             const bool last = (t == nt - 2);
;             const char* a1 = cA + (size_t)(t + 1) * kstep;
;             const char* a2 = last ? nA : cA + (size_t)(t + 2) * kstep; const char* b2 = last ? nB : cB + (size_t)(t + 2) * kstep;
;             const char* a3 = a2 + kstep; const char* b3 = b2 + kstep;
;             if (last && has_next) S.a_ready(nxt);
;             if constexpr (SP2) {
;             PG8_LDB(B0, 0, 0); PG8_LDB(B1, 0, 1); PG8_SCHED; PG8_LDA(At, 0, 0); PG8_STAGE(PG8_SA(1, 1), a1 + hstep, voffA);
;             PG8_WAIT_V(8); PG8_WAIT_L(0); PG8_BAR; PG8_MMA(0, 0, At, B0); PG8_MMA(0, 1, At, B1); PG8_BAR; PG8_SCHED;
;             PG8_LDA(At, 0, 1); PG8_STAGE(PG8_SB(0, 0), b2, voffB); PG8_STAGE(PG8_SB(0, 1), b2 + hstep, voffB); PG8_STAGE(PG8_SA(0, 0), a2, voffA);
;             PG8_WAIT_V(8); PG8_WAIT_L(0); PG8_BAR; PG8_MMA(1, 0, At, B0); PG8_MMA(1, 1, At, B1); PG8_BAR; PG8_SCHED;
;             PG8_LDB(B0, 1, 0); PG8_LDB(B1, 1, 1); PG8_SCHED; PG8_LDA(At, 1, 0); PG8_STAGE(PG8_SA(0, 1), a2 + hstep, voffA);
;             PG8_WAIT_V(8); PG8_WAIT_L(0); PG8_BAR; PG8_MMA(0, 0, At, B0); PG8_MMA(0, 1, At, B1); PG8_BAR; PG8_SCHED;
;             PG8_LDA(At, 1, 1); PG8_STAGE(PG8_SB(1, 0), b3, voffB); PG8_STAGE(PG8_SB(1, 1), b3 + hstep, voffB); PG8_STAGE(PG8_SA(1, 0), a3, voffA);
;             PG8_WAIT_V(8); PG8_WAIT_L(0); PG8_BAR; PG8_MMA(1, 0, At, B0); PG8_MMA(1, 1, At, B1); PG8_BAR; PG8_SCHED;
	s_add_i32 s49, 0, 0x18000
	s_add_i32 s50, 0, 0x1c000
	v_add_u32_e32 v162, s49, v145
	v_add_u32_e32 v172, s50, v145
	ds_read_b128 v[150:153], v162
	ds_read_b128 v[154:157], v162 offset:1024
	ds_read_b128 v[158:161], v162 offset:2048
	ds_read_b128 v[162:165], v162 offset:3072
	ds_read_b128 v[166:169], v172
	ds_read_b128 v[176:179], v172 offset:1024
	ds_read_b128 v[180:183], v172 offset:2048
	ds_read_b128 v[184:187], v172 offset:3072
	s_add_u32 s30, s30, 0x40000
	s_addc_u32 s31, s31, 0
	s_mov_b32 m0, s37
	ds_read_b128 v[188:191], v149 offset:32768
	ds_read_b128 v[192:195], v149 offset:33792
	ds_read_b128 v[196:199], v149 offset:34816
	ds_read_b128 v[200:203], v149 offset:35840
	ds_read_b128 v[204:207], v149 offset:36864
	ds_read_b128 v[208:211], v149 offset:37888
	ds_read_b128 v[212:215], v149 offset:38912
	ds_read_b128 v[216:219], v149 offset:39936
	global_load_lds_dwordx4 v130, s[30:31]
	s_mov_b32 m0, s40
	s_nop 0
	global_load_lds_dwordx4 v134, s[30:31]
	s_waitcnt vmcnt(8)
	s_waitcnt lgkmcnt(0)
	s_barrier
	s_setprio 1
	s_waitcnt lgkmcnt(0)
	v_mfma_f32_16x16x32_bf16 v[126:129], v[150:153], v[188:191], v[126:129]
	v_mfma_f32_16x16x32_bf16 v[122:125], v[158:161], v[188:191], v[122:125]
	v_mfma_f32_16x16x32_bf16 v[110:113], v[150:153], v[196:199], v[110:113]
	v_mfma_f32_16x16x32_bf16 v[106:109], v[158:161], v[196:199], v[106:109]
	v_mfma_f32_16x16x32_bf16 v[94:97], v[150:153], v[204:207], v[94:97]
	v_mfma_f32_16x16x32_bf16 v[90:93], v[158:161], v[204:207], v[90:93]
	v_mfma_f32_16x16x32_bf16 v[78:81], v[150:153], v[212:215], v[78:81]
	v_mfma_f32_16x16x32_bf16 v[74:77], v[158:161], v[212:215], v[74:77]
	v_mfma_f32_16x16x32_bf16 v[126:129], v[154:157], v[192:195], v[126:129]
	v_mfma_f32_16x16x32_bf16 v[122:125], v[162:165], v[192:195], v[122:125]
	v_mfma_f32_16x16x32_bf16 v[110:113], v[154:157], v[200:203], v[110:113]
	v_mfma_f32_16x16x32_bf16 v[106:109], v[162:165], v[200:203], v[106:109]
	v_mfma_f32_16x16x32_bf16 v[94:97], v[154:157], v[208:211], v[94:97]
	v_mfma_f32_16x16x32_bf16 v[90:93], v[162:165], v[208:211], v[90:93]
	v_mfma_f32_16x16x32_bf16 v[78:81], v[154:157], v[216:219], v[78:81]
	v_mfma_f32_16x16x32_bf16 v[74:77], v[162:165], v[216:219], v[74:77]
	v_mfma_f32_16x16x32_bf16 v[118:121], v[166:169], v[188:191], v[118:121]
	v_mfma_f32_16x16x32_bf16 v[114:117], v[180:183], v[188:191], v[114:117]
	v_mfma_f32_16x16x32_bf16 v[102:105], v[166:169], v[196:199], v[102:105]
	v_mfma_f32_16x16x32_bf16 v[98:101], v[180:183], v[196:199], v[98:101]
	v_mfma_f32_16x16x32_bf16 v[86:89], v[166:169], v[204:207], v[86:89]
	v_mfma_f32_16x16x32_bf16 v[82:85], v[180:183], v[204:207], v[82:85]
	v_mfma_f32_16x16x32_bf16 v[70:73], v[166:169], v[212:215], v[70:73]
	v_mfma_f32_16x16x32_bf16 v[66:69], v[180:183], v[212:215], v[66:69]
	v_mfma_f32_16x16x32_bf16 v[118:121], v[176:179], v[192:195], v[118:121]
	v_mfma_f32_16x16x32_bf16 v[114:117], v[184:187], v[192:195], v[114:117]
	v_mfma_f32_16x16x32_bf16 v[102:105], v[176:179], v[200:203], v[102:105]
	v_mfma_f32_16x16x32_bf16 v[98:101], v[184:187], v[200:203], v[98:101]
	v_mfma_f32_16x16x32_bf16 v[86:89], v[176:179], v[208:211], v[86:89]
	v_mfma_f32_16x16x32_bf16 v[82:85], v[184:187], v[208:211], v[82:85]
	v_mfma_f32_16x16x32_bf16 v[70:73], v[176:179], v[216:219], v[70:73]
	v_mfma_f32_16x16x32_bf16 v[66:69], v[184:187], v[216:219], v[66:69]
	s_setprio 0
	s_barrier
	s_add_i32 s30, s49, s6
	s_mov_b32 m0, s30
	ds_read_b128 v[188:191], v149 offset:49152
	ds_read_b128 v[192:195], v149 offset:50176
	ds_read_b128 v[196:199], v149 offset:51200
	ds_read_b128 v[200:203], v149 offset:52224
	ds_read_b128 v[204:207], v149 offset:53248
	ds_read_b128 v[208:211], v149 offset:54272
	ds_read_b128 v[212:215], v149 offset:55296
	ds_read_b128 v[216:219], v149 offset:56320
	s_add_u32 s98, s28, 0x80
	s_addc_u32 s99, s29, 0
	global_load_lds_dwordx4 v132, s[98:99]
	s_add_i32 m0, s30, 0x2000
	s_add_u32 s28, s28, 0x40080
	v_lshl_add_u64 v[142:143], v[170:171], 0, s[92:93]
	s_addc_u32 s29, s29, 0
	s_add_i32 s30, s50, s6
	global_load_lds_dwordx4 v[142:143], off
	s_mov_b32 m0, s30
	s_nop 0
	global_load_lds_dwordx4 v132, s[28:29]
	s_add_i32 m0, s30, 0x2000
	s_nop 0
	global_load_lds_dwordx4 v136, s[28:29]
	v_lshl_add_u64 v[142:143], v[220:221], 0, s[92:93]
	s_mov_b32 m0, s41
	s_nop 0
	global_load_lds_dwordx4 v[142:143], off
	v_lshl_add_u64 v[142:143], v[222:223], 0, s[92:93]
	s_mov_b32 m0, s42
	s_nop 0
	global_load_lds_dwordx4 v[142:143], off
	s_waitcnt vmcnt(8)
	s_waitcnt lgkmcnt(0)
	s_barrier
	s_setprio 1
	s_waitcnt lgkmcnt(0)
	v_mfma_f32_16x16x32_bf16 v[60:63], v[150:153], v[188:191], v[60:63]
	v_mfma_f32_16x16x32_bf16 v[56:59], v[158:161], v[188:191], v[56:59]
	v_mfma_f32_16x16x32_bf16 v[44:47], v[150:153], v[196:199], v[44:47]
	v_mfma_f32_16x16x32_bf16 v[40:43], v[158:161], v[196:199], v[40:43]
	v_mfma_f32_16x16x32_bf16 v[28:31], v[150:153], v[204:207], v[28:31]
	v_mfma_f32_16x16x32_bf16 v[24:27], v[158:161], v[204:207], v[24:27]
	v_mfma_f32_16x16x32_bf16 v[12:15], v[150:153], v[212:215], v[12:15]
	v_mfma_f32_16x16x32_bf16 v[8:11], v[158:161], v[212:215], v[8:11]
	v_mfma_f32_16x16x32_bf16 v[60:63], v[154:157], v[192:195], v[60:63]
	v_mfma_f32_16x16x32_bf16 v[56:59], v[162:165], v[192:195], v[56:59]
	v_mfma_f32_16x16x32_bf16 v[44:47], v[154:157], v[200:203], v[44:47]
	v_mfma_f32_16x16x32_bf16 v[40:43], v[162:165], v[200:203], v[40:43]
	v_mfma_f32_16x16x32_bf16 v[28:31], v[154:157], v[208:211], v[28:31]
	v_mfma_f32_16x16x32_bf16 v[24:27], v[162:165], v[208:211], v[24:27]
	v_mfma_f32_16x16x32_bf16 v[12:15], v[154:157], v[216:219], v[12:15]
	v_mfma_f32_16x16x32_bf16 v[8:11], v[162:165], v[216:219], v[8:11]
	v_mfma_f32_16x16x32_bf16 v[52:55], v[166:169], v[188:191], v[52:55]
	v_mfma_f32_16x16x32_bf16 v[48:51], v[180:183], v[188:191], v[48:51]
	v_mfma_f32_16x16x32_bf16 v[36:39], v[166:169], v[196:199], v[36:39]
	v_mfma_f32_16x16x32_bf16 v[32:35], v[180:183], v[196:199], v[32:35]
	v_mfma_f32_16x16x32_bf16 v[20:23], v[166:169], v[204:207], v[20:23]
	v_mfma_f32_16x16x32_bf16 v[16:19], v[180:183], v[204:207], v[16:19]
	v_mfma_f32_16x16x32_bf16 v[4:7], v[166:169], v[212:215], v[4:7]
	v_mfma_f32_16x16x32_bf16 v[0:3], v[180:183], v[212:215], v[0:3]
	v_mfma_f32_16x16x32_bf16 v[52:55], v[176:179], v[192:195], v[52:55]
	v_mfma_f32_16x16x32_bf16 v[48:51], v[184:187], v[192:195], v[48:51]
	v_mfma_f32_16x16x32_bf16 v[36:39], v[176:179], v[200:203], v[36:39]
	v_mfma_f32_16x16x32_bf16 v[32:35], v[184:187], v[200:203], v[32:35]
	v_mfma_f32_16x16x32_bf16 v[20:23], v[176:179], v[208:211], v[20:23]
	v_mfma_f32_16x16x32_bf16 v[16:19], v[184:187], v[208:211], v[16:19]
	v_mfma_f32_16x16x32_bf16 v[4:7], v[176:179], v[216:219], v[4:7]
	v_mfma_f32_16x16x32_bf16 v[0:3], v[184:187], v[216:219], v[0:3]
	s_setprio 0
	s_barrier
	s_add_i32 s48, s48, 2
	s_add_u32 s26, s26, 0x100
	s_addc_u32 s27, s27, 0
	s_add_u32 s46, s46, 0x100
	s_addc_u32 s47, s47, 0
	s_cmp_gt_u32 s48, 13
	s_cbranch_scc0 .LBB0_754
